# combo2 + MFMA issue order regrouped so the B-fragment operand stays fixed for 4 consecutive MFMAs
# baseline (speedup 1.0000x reference)
; #define PG8_STAGE(bufoff, gbase, voff) do { _Pragma("unroll") for (int _i = 0; _i < 2; ++_i) \
;         __builtin_amdgcn_global_load_lds((const unsigned*)((const char*)(gbase) + (voff)[_i]), (PG8_LAS unsigned*)(lds + (bufoff) + ldsw + _i * 8192), 16, 0, 0); } while (0)
; #define PG8_LDA(dst, b, h) do { _Pragma("unroll") for (int m = 0; m < 4; ++m) _Pragma("unroll") for (int k = 0; k < 2; ++k) dst[m][k] = *(const PG8_LAS bf16x8*)(lds + PG8_SA(b, h) + aoff + m * 2048 + k * 1024); } while (0)
; #define PG8_LDB(dst, b, h) do { _Pragma("unroll") for (int n = 0; n < 2; ++n) _Pragma("unroll") for (int k = 0; k < 2; ++k) dst[n][k] = *(const PG8_LAS bf16x8*)(lds + PG8_SB(b, h) + boff + n * 2048 + k * 1024); } while (0)
; #define PG8_MMA(ai, bj, At, Bt) do { __builtin_amdgcn_s_setprio(1); _Pragma("unroll") for (int m = 0; m < 4; ++m) _Pragma("unroll") for (int n = 0; n < 2; ++n) _Pragma("unroll") for (int k = 0; k < 2; ++k) \
;         acc[ai][bj][m][n] = __builtin_amdgcn_mfma_f32_16x16x32_bf16(Bt[n][k], At[m][k], acc[ai][bj][m][n], 0, 0, 0); __builtin_amdgcn_s_setprio(0); } while (0)
; #define PG8_WAIT_V(n) asm volatile("s_waitcnt vmcnt(" #n ")" ::: "memory")
; #define PG8_WAIT_L(n) asm volatile("s_waitcnt lgkmcnt(" #n ")" ::: "memory")
; #define PG8_BAR __builtin_amdgcn_s_barrier()
; #define PG8_SCHED __builtin_amdgcn_sched_barrier(0)
; template <class Epi, class Sched, bool ALIGN_EPI = false, bool SP2 = false>
; __device__ __forceinline__ void gemm_phase(PG8_LAS unsigned char* lds, const Gemm g, const Sched& S, const Epi& E, const int tid) {
;     ...
;             const char* a1 = cA + (size_t)(t + 1) * kstep;
;             const char* a2 = last ? nA : cA + (size_t)(t + 2) * kstep; const char* b2 = last ? nB : cB + (size_t)(t + 2) * kstep;
;             const char* a3 = a2 + kstep; const char* b3 = b2 + kstep;
;             if (last && has_next) S.a_ready(nxt);
;             if (last) E.prefetch(lds + EPI_LDS_OFF + wid * 1024, cur, wr, wc, lane);
;             if constexpr (SP2) {
;             PG8_LDB(B0, 0, 0); PG8_LDB(B1, 0, 1); PG8_SCHED; PG8_LDA(At, 0, 0); PG8_STAGE(PG8_SA(1, 1), a1 + hstep, voffA);
;             PG8_WAIT_V(8); PG8_WAIT_L(0); PG8_BAR; PG8_MMA(0, 0, At, B0); PG8_MMA(0, 1, At, B1); PG8_BAR; PG8_SCHED;
;             PG8_LDA(At, 0, 1); PG8_STAGE(PG8_SB(0, 0), b2, voffB); PG8_STAGE(PG8_SB(0, 1), b2 + hstep, voffB); PG8_STAGE(PG8_SA(0, 0), a2, voffA);
.LBB0_42:
	s_add_u32 s18, s16, 0x100
	s_addc_u32 s19, s17, 0
	s_and_b64 s[20:21], s[20:21], exec
	s_cselect_b32 s23, s9, s19
	s_cselect_b32 s22, s8, s18
	s_cselect_b32 s21, s15, s74
	s_cselect_b32 s20, s14, s55
	s_add_i32 s3, 0, 0x10000
	s_add_i32 s42, 0, 0x14000
	v_add_u32_e32 v146, s3, v224
	v_add_u32_e32 v162, s42, v224
	ds_read_b128 v[134:137], v146
	ds_read_b128 v[138:141], v146 offset:1024
	ds_read_b128 v[142:145], v146 offset:2048
	ds_read_b128 v[146:149], v146 offset:3072
	ds_read_b128 v[150:153], v162
	ds_read_b128 v[154:157], v162 offset:1024
	ds_read_b128 v[158:161], v162 offset:2048
	ds_read_b128 v[172:175], v162 offset:3072
	v_lshl_add_u64 v[162:163], s[16:17], 0, v[168:169]
	s_add_i32 m0, s27, 0xc000
	ds_read_b128 v[176:179], v228
	ds_read_b128 v[180:183], v228 offset:1024
	ds_read_b128 v[186:189], v228 offset:2048
	ds_read_b128 v[190:193], v228 offset:3072
	ds_read_b128 v[194:197], v228 offset:4096
	ds_read_b128 v[198:201], v228 offset:5120
	ds_read_b128 v[202:205], v228 offset:6144
	ds_read_b128 v[206:209], v228 offset:7168
	global_load_lds_dwordx4 v[162:163], off
	v_lshl_add_u64 v[162:163], s[16:17], 0, v[170:171]
	s_add_i32 m0, s27, 0xe000
	s_nop 0
	global_load_lds_dwordx4 v[162:163], off
	s_waitcnt vmcnt(8)
	s_waitcnt lgkmcnt(0)
	s_setprio 1
	s_barrier
	v_mfma_f32_16x16x32_bf16 v[128:131], v[134:137], v[176:179], v[128:131]
	v_mfma_f32_16x16x32_bf16 v[112:115], v[134:137], v[186:189], v[112:115]
	v_mfma_f32_16x16x32_bf16 v[96:99], v[134:137], v[194:197], v[96:99]
	v_mfma_f32_16x16x32_bf16 v[80:83], v[134:137], v[202:205], v[80:83]
	v_mfma_f32_16x16x32_bf16 v[124:127], v[142:145], v[176:179], v[124:127]
	v_mfma_f32_16x16x32_bf16 v[108:111], v[142:145], v[186:189], v[108:111]
	v_mfma_f32_16x16x32_bf16 v[92:95], v[142:145], v[194:197], v[92:95]
	v_mfma_f32_16x16x32_bf16 v[76:79], v[142:145], v[202:205], v[76:79]
	v_mfma_f32_16x16x32_bf16 v[128:131], v[138:141], v[180:183], v[128:131]
	v_mfma_f32_16x16x32_bf16 v[112:115], v[138:141], v[190:193], v[112:115]
	v_mfma_f32_16x16x32_bf16 v[96:99], v[138:141], v[198:201], v[96:99]
	v_mfma_f32_16x16x32_bf16 v[80:83], v[138:141], v[206:209], v[80:83]
	v_mfma_f32_16x16x32_bf16 v[124:127], v[146:149], v[180:183], v[124:127]
	v_mfma_f32_16x16x32_bf16 v[108:111], v[146:149], v[190:193], v[108:111]
	v_mfma_f32_16x16x32_bf16 v[92:95], v[146:149], v[198:201], v[92:95]
	v_mfma_f32_16x16x32_bf16 v[76:79], v[146:149], v[206:209], v[76:79]
	s_setprio 0
	s_setprio 1
	v_mfma_f32_16x16x32_bf16 v[120:123], v[150:153], v[176:179], v[120:123]
	v_mfma_f32_16x16x32_bf16 v[104:107], v[150:153], v[186:189], v[104:107]
	v_mfma_f32_16x16x32_bf16 v[88:91], v[150:153], v[194:197], v[88:91]
	v_mfma_f32_16x16x32_bf16 v[72:75], v[150:153], v[202:205], v[72:75]
	v_mfma_f32_16x16x32_bf16 v[116:119], v[158:161], v[176:179], v[116:119]
	v_mfma_f32_16x16x32_bf16 v[100:103], v[158:161], v[186:189], v[100:103]
	v_mfma_f32_16x16x32_bf16 v[84:87], v[158:161], v[194:197], v[84:87]
	v_mfma_f32_16x16x32_bf16 v[68:71], v[158:161], v[202:205], v[68:71]
	v_mfma_f32_16x16x32_bf16 v[120:123], v[154:157], v[180:183], v[120:123]
	v_mfma_f32_16x16x32_bf16 v[104:107], v[154:157], v[190:193], v[104:107]
	v_mfma_f32_16x16x32_bf16 v[88:91], v[154:157], v[198:201], v[88:91]
	v_mfma_f32_16x16x32_bf16 v[72:75], v[154:157], v[206:209], v[72:75]
	v_mfma_f32_16x16x32_bf16 v[116:119], v[172:175], v[180:183], v[116:119]
	v_mfma_f32_16x16x32_bf16 v[100:103], v[172:175], v[190:193], v[100:103]
	v_mfma_f32_16x16x32_bf16 v[84:87], v[172:175], v[198:201], v[84:87]
	v_mfma_f32_16x16x32_bf16 v[68:71], v[172:175], v[206:209], v[68:71]
	s_setprio 0
	s_barrier
	s_add_i32 s3, s3, s26
	v_lshl_add_u64 v[162:163], s[20:21], 0, v[2:3]
	s_mov_b32 m0, s3
	ds_read_b128 v[176:179], v228 offset:16384
	ds_read_b128 v[180:183], v228 offset:17408
	ds_read_b128 v[186:189], v228 offset:18432
	ds_read_b128 v[190:193], v228 offset:19456
	ds_read_b128 v[194:197], v228 offset:20480
	ds_read_b128 v[198:201], v228 offset:21504
	ds_read_b128 v[202:205], v228 offset:22528
	ds_read_b128 v[206:209], v228 offset:23552
	global_load_lds_dwordx4 v[162:163], off
	s_add_i32 m0, s3, 0x2000
	s_add_u32 s16, s20, 0x160000
	v_lshl_add_u64 v[210:211], s[20:21], 0, v[166:167]
	s_addc_u32 s17, s21, 0
	s_add_i32 s3, s42, s26
	global_load_lds_dwordx4 v[210:211], off
	v_lshl_add_u64 v[212:213], s[16:17], 0, v[2:3]
	s_mov_b32 m0, s3
	v_lshl_add_u64 v[214:215], s[22:23], 0, v[164:165]
	global_load_lds_dwordx4 v[212:213], off
	v_lshl_add_u64 v[212:213], s[16:17], 0, v[166:167]
	s_add_i32 m0, s3, 0x2000
	s_nop 0
	global_load_lds_dwordx4 v[212:213], off
	v_lshl_add_u64 v[212:213], s[22:23], 0, v[0:1]
	s_mov_b32 m0, s27
	s_nop 0
	global_load_lds_dwordx4 v[212:213], off
	s_mov_b32 m0, s28
	s_nop 0
	global_load_lds_dwordx4 v[214:215], off
	s_waitcnt vmcnt(8)
	s_waitcnt lgkmcnt(0)
	s_setprio 1
	s_barrier
; #define PG8_STAGE(bufoff, gbase, voff) do { _Pragma("unroll") for (int _i = 0; _i < 2; ++_i) \
;         __builtin_amdgcn_global_load_lds((const unsigned*)((const char*)(gbase) + (voff)[_i]), (PG8_LAS unsigned*)(lds + (bufoff) + ldsw + _i * 8192), 16, 0, 0); } while (0)
; #define PG8_LDA(dst, b, h) do { _Pragma("unroll") for (int m = 0; m < 4; ++m) _Pragma("unroll") for (int k = 0; k < 2; ++k) dst[m][k] = *(const PG8_LAS bf16x8*)(lds + PG8_SA(b, h) + aoff + m * 2048 + k * 1024); } while (0)
; #define PG8_LDB(dst, b, h) do { _Pragma("unroll") for (int n = 0; n < 2; ++n) _Pragma("unroll") for (int k = 0; k < 2; ++k) dst[n][k] = *(const PG8_LAS bf16x8*)(lds + PG8_SB(b, h) + boff + n * 2048 + k * 1024); } while (0)
; #define PG8_MMA(ai, bj, At, Bt) do { __builtin_amdgcn_s_setprio(1); _Pragma("unroll") for (int m = 0; m < 4; ++m) _Pragma("unroll") for (int n = 0; n < 2; ++n) _Pragma("unroll") for (int k = 0; k < 2; ++k) \
;         acc[ai][bj][m][n] = __builtin_amdgcn_mfma_f32_16x16x32_bf16(Bt[n][k], At[m][k], acc[ai][bj][m][n], 0, 0, 0); __builtin_amdgcn_s_setprio(0); } while (0)
; #define PG8_WAIT_V(n) asm volatile("s_waitcnt vmcnt(" #n ")" ::: "memory")
; #define PG8_WAIT_L(n) asm volatile("s_waitcnt lgkmcnt(" #n ")" ::: "memory")
; #define PG8_BAR __builtin_amdgcn_s_barrier()
; #define PG8_SCHED __builtin_amdgcn_sched_barrier(0)
; template <class Epi, class Sched, bool ALIGN_EPI = false, bool SP2 = false>
; __device__ __forceinline__ void gemm_phase(PG8_LAS unsigned char* lds, const Gemm g, const Sched& S, const Epi& E, const int tid) {
;     ...
;             PG8_WAIT_V(8); PG8_WAIT_L(0); PG8_BAR; PG8_MMA(1, 0, At, B0); PG8_MMA(1, 1, At, B1); PG8_BAR; PG8_SCHED;
;             PG8_LDB(B0, 1, 0); PG8_LDB(B1, 1, 1); PG8_SCHED; PG8_LDA(At, 1, 0); PG8_STAGE(PG8_SA(0, 1), a2 + hstep, voffA);
;             PG8_WAIT_V(8); PG8_WAIT_L(0); PG8_BAR; PG8_MMA(0, 0, At, B0); PG8_MMA(0, 1, At, B1); PG8_BAR; PG8_SCHED;
	v_mfma_f32_16x16x32_bf16 v[64:67], v[134:137], v[176:179], v[64:67]
	v_mfma_f32_16x16x32_bf16 v[48:51], v[134:137], v[186:189], v[48:51]
	v_mfma_f32_16x16x32_bf16 v[32:35], v[134:137], v[194:197], v[32:35]
	v_mfma_f32_16x16x32_bf16 v[16:19], v[134:137], v[202:205], v[16:19]
	v_mfma_f32_16x16x32_bf16 v[60:63], v[142:145], v[176:179], v[60:63]
	v_mfma_f32_16x16x32_bf16 v[44:47], v[142:145], v[186:189], v[44:47]
	v_mfma_f32_16x16x32_bf16 v[28:31], v[142:145], v[194:197], v[28:31]
	v_mfma_f32_16x16x32_bf16 v[12:15], v[142:145], v[202:205], v[12:15]
	v_mfma_f32_16x16x32_bf16 v[64:67], v[138:141], v[180:183], v[64:67]
	v_mfma_f32_16x16x32_bf16 v[48:51], v[138:141], v[190:193], v[48:51]
	v_mfma_f32_16x16x32_bf16 v[32:35], v[138:141], v[198:201], v[32:35]
	v_mfma_f32_16x16x32_bf16 v[16:19], v[138:141], v[206:209], v[16:19]
	v_mfma_f32_16x16x32_bf16 v[60:63], v[146:149], v[180:183], v[60:63]
	v_mfma_f32_16x16x32_bf16 v[44:47], v[146:149], v[190:193], v[44:47]
	v_mfma_f32_16x16x32_bf16 v[28:31], v[146:149], v[198:201], v[28:31]
	v_mfma_f32_16x16x32_bf16 v[12:15], v[146:149], v[206:209], v[12:15]
	s_setprio 0
	s_setprio 1
	v_mfma_f32_16x16x32_bf16 v[56:59], v[150:153], v[176:179], v[56:59]
	v_mfma_f32_16x16x32_bf16 v[40:43], v[150:153], v[186:189], v[40:43]
	v_mfma_f32_16x16x32_bf16 v[24:27], v[150:153], v[194:197], v[24:27]
	v_mfma_f32_16x16x32_bf16 v[8:11], v[150:153], v[202:205], v[8:11]
	v_mfma_f32_16x16x32_bf16 v[52:55], v[158:161], v[176:179], v[52:55]
	v_mfma_f32_16x16x32_bf16 v[36:39], v[158:161], v[186:189], v[36:39]
	v_mfma_f32_16x16x32_bf16 v[20:23], v[158:161], v[194:197], v[20:23]
	v_mfma_f32_16x16x32_bf16 v[4:7], v[158:161], v[202:205], v[4:7]
	v_mfma_f32_16x16x32_bf16 v[56:59], v[154:157], v[180:183], v[56:59]
	v_mfma_f32_16x16x32_bf16 v[40:43], v[154:157], v[190:193], v[40:43]
	v_mfma_f32_16x16x32_bf16 v[24:27], v[154:157], v[198:201], v[24:27]
	v_mfma_f32_16x16x32_bf16 v[8:11], v[154:157], v[206:209], v[8:11]
	v_mfma_f32_16x16x32_bf16 v[52:55], v[172:175], v[180:183], v[52:55]
	v_mfma_f32_16x16x32_bf16 v[36:39], v[172:175], v[190:193], v[36:39]
	v_mfma_f32_16x16x32_bf16 v[20:23], v[172:175], v[198:201], v[20:23]
	v_mfma_f32_16x16x32_bf16 v[4:7], v[172:175], v[206:209], v[4:7]
	s_setprio 0
	s_barrier
	s_add_i32 s3, 0, 0x18000
	s_add_i32 s42, 0, 0x1c000
	v_add_u32_e32 v146, s3, v224
	v_add_u32_e32 v172, s42, v224
	ds_read_b128 v[134:137], v146
	ds_read_b128 v[138:141], v146 offset:1024
	ds_read_b128 v[142:145], v146 offset:2048
	ds_read_b128 v[146:149], v146 offset:3072
	ds_read_b128 v[150:153], v172
	ds_read_b128 v[154:157], v172 offset:1024
	ds_read_b128 v[158:161], v172 offset:2048
	ds_read_b128 v[172:175], v172 offset:3072
	s_add_u32 s16, s22, 0x160000
	s_addc_u32 s17, s23, 0
	s_mov_b32 m0, s29
	v_lshl_add_u64 v[216:217], s[16:17], 0, v[0:1]
	ds_read_b128 v[176:179], v228 offset:32768
	ds_read_b128 v[180:183], v228 offset:33792
	ds_read_b128 v[186:189], v228 offset:34816
	ds_read_b128 v[190:193], v228 offset:35840
	ds_read_b128 v[194:197], v228 offset:36864
	ds_read_b128 v[198:201], v228 offset:37888
	ds_read_b128 v[202:205], v228 offset:38912
	ds_read_b128 v[206:209], v228 offset:39936
	global_load_lds_dwordx4 v[216:217], off
	v_lshl_add_u64 v[216:217], s[16:17], 0, v[164:165]
	s_mov_b32 m0, s30
	s_nop 0
	global_load_lds_dwordx4 v[216:217], off
	s_waitcnt vmcnt(8)
	s_waitcnt lgkmcnt(0)
	s_setprio 1
	s_barrier
	v_mfma_f32_16x16x32_bf16 v[128:131], v[134:137], v[176:179], v[128:131]
	v_mfma_f32_16x16x32_bf16 v[112:115], v[134:137], v[186:189], v[112:115]
	v_mfma_f32_16x16x32_bf16 v[96:99], v[134:137], v[194:197], v[96:99]
	v_mfma_f32_16x16x32_bf16 v[80:83], v[134:137], v[202:205], v[80:83]
	v_mfma_f32_16x16x32_bf16 v[124:127], v[142:145], v[176:179], v[124:127]
	v_mfma_f32_16x16x32_bf16 v[108:111], v[142:145], v[186:189], v[108:111]
	v_mfma_f32_16x16x32_bf16 v[92:95], v[142:145], v[194:197], v[92:95]
	v_mfma_f32_16x16x32_bf16 v[76:79], v[142:145], v[202:205], v[76:79]
	v_mfma_f32_16x16x32_bf16 v[128:131], v[138:141], v[180:183], v[128:131]
	v_mfma_f32_16x16x32_bf16 v[112:115], v[138:141], v[190:193], v[112:115]
	v_mfma_f32_16x16x32_bf16 v[96:99], v[138:141], v[198:201], v[96:99]
	v_mfma_f32_16x16x32_bf16 v[80:83], v[138:141], v[206:209], v[80:83]
	v_mfma_f32_16x16x32_bf16 v[124:127], v[146:149], v[180:183], v[124:127]
	v_mfma_f32_16x16x32_bf16 v[108:111], v[146:149], v[190:193], v[108:111]
	v_mfma_f32_16x16x32_bf16 v[92:95], v[146:149], v[198:201], v[92:95]
	v_mfma_f32_16x16x32_bf16 v[76:79], v[146:149], v[206:209], v[76:79]
	s_setprio 0
	s_setprio 1
	v_mfma_f32_16x16x32_bf16 v[120:123], v[150:153], v[176:179], v[120:123]
	v_mfma_f32_16x16x32_bf16 v[104:107], v[150:153], v[186:189], v[104:107]
	v_mfma_f32_16x16x32_bf16 v[88:91], v[150:153], v[194:197], v[88:91]
	v_mfma_f32_16x16x32_bf16 v[72:75], v[150:153], v[202:205], v[72:75]
	v_mfma_f32_16x16x32_bf16 v[116:119], v[158:161], v[176:179], v[116:119]
	v_mfma_f32_16x16x32_bf16 v[100:103], v[158:161], v[186:189], v[100:103]
	v_mfma_f32_16x16x32_bf16 v[84:87], v[158:161], v[194:197], v[84:87]
	v_mfma_f32_16x16x32_bf16 v[68:71], v[158:161], v[202:205], v[68:71]
	v_mfma_f32_16x16x32_bf16 v[120:123], v[154:157], v[180:183], v[120:123]
	v_mfma_f32_16x16x32_bf16 v[104:107], v[154:157], v[190:193], v[104:107]
	v_mfma_f32_16x16x32_bf16 v[88:91], v[154:157], v[198:201], v[88:91]
	v_mfma_f32_16x16x32_bf16 v[72:75], v[154:157], v[206:209], v[72:75]
	v_mfma_f32_16x16x32_bf16 v[116:119], v[172:175], v[180:183], v[116:119]
	v_mfma_f32_16x16x32_bf16 v[100:103], v[172:175], v[190:193], v[100:103]
	v_mfma_f32_16x16x32_bf16 v[84:87], v[172:175], v[198:201], v[84:87]
	v_mfma_f32_16x16x32_bf16 v[68:71], v[172:175], v[206:209], v[68:71]
	s_setprio 0
	s_barrier
; #define PG8_STAGE(bufoff, gbase, voff) do { _Pragma("unroll") for (int _i = 0; _i < 2; ++_i) \
;         __builtin_amdgcn_global_load_lds((const unsigned*)((const char*)(gbase) + (voff)[_i]), (PG8_LAS unsigned*)(lds + (bufoff) + ldsw + _i * 8192), 16, 0, 0); } while (0)
; #define PG8_LDA(dst, b, h) do { _Pragma("unroll") for (int m = 0; m < 4; ++m) _Pragma("unroll") for (int k = 0; k < 2; ++k) dst[m][k] = *(const PG8_LAS bf16x8*)(lds + PG8_SA(b, h) + aoff + m * 2048 + k * 1024); } while (0)
; #define PG8_MMA(ai, bj, At, Bt) do { __builtin_amdgcn_s_setprio(1); _Pragma("unroll") for (int m = 0; m < 4; ++m) _Pragma("unroll") for (int n = 0; n < 2; ++n) _Pragma("unroll") for (int k = 0; k < 2; ++k) \
;         acc[ai][bj][m][n] = __builtin_amdgcn_mfma_f32_16x16x32_bf16(Bt[n][k], At[m][k], acc[ai][bj][m][n], 0, 0, 0); __builtin_amdgcn_s_setprio(0); } while (0)
; #define PG8_WAIT_V(n) asm volatile("s_waitcnt vmcnt(" #n ")" ::: "memory")
; #define PG8_WAIT_L(n) asm volatile("s_waitcnt lgkmcnt(" #n ")" ::: "memory")
; #define PG8_BAR __builtin_amdgcn_s_barrier()
; #define PG8_SCHED __builtin_amdgcn_sched_barrier(0)
; template <class Epi, class Sched, bool ALIGN_EPI = false, bool SP2 = false>
; __device__ __forceinline__ void gemm_phase(PG8_LAS unsigned char* lds, const Gemm g, const Sched& S, const Epi& E, const int tid) {
;     ...
;             PG8_LDA(At, 1, 1); PG8_STAGE(PG8_SB(1, 0), b3, voffB); PG8_STAGE(PG8_SB(1, 1), b3 + hstep, voffB); PG8_STAGE(PG8_SA(1, 0), a3, voffA);
;             PG8_WAIT_V(8); PG8_WAIT_L(0); PG8_BAR; PG8_MMA(1, 0, At, B0); PG8_MMA(1, 1, At, B1); PG8_BAR; PG8_SCHED;
	s_add_i32 s3, s3, s26
	v_lshl_add_u64 v[162:163], v[162:163], 0, s[46:47]
	s_mov_b32 m0, s3
	ds_read_b128 v[176:179], v228 offset:49152
	ds_read_b128 v[180:183], v228 offset:50176
	ds_read_b128 v[186:189], v228 offset:51200
	ds_read_b128 v[190:193], v228 offset:52224
	ds_read_b128 v[194:197], v228 offset:53248
	ds_read_b128 v[198:201], v228 offset:54272
	ds_read_b128 v[202:205], v228 offset:55296
	ds_read_b128 v[206:209], v228 offset:56320
	global_load_lds_dwordx4 v[162:163], off
	s_add_i32 m0, s3, 0x2000
	s_add_u32 s16, s20, 0x160080
	v_lshl_add_u64 v[162:163], v[210:211], 0, s[46:47]
	s_addc_u32 s17, s21, 0
	s_add_i32 s3, s42, s26
	global_load_lds_dwordx4 v[162:163], off
	v_lshl_add_u64 v[162:163], s[16:17], 0, v[2:3]
	s_mov_b32 m0, s3
	s_nop 0
	global_load_lds_dwordx4 v[162:163], off
	v_lshl_add_u64 v[162:163], s[16:17], 0, v[166:167]
	s_add_i32 m0, s3, 0x2000
	s_nop 0
	global_load_lds_dwordx4 v[162:163], off
	v_lshl_add_u64 v[162:163], v[212:213], 0, s[46:47]
	s_mov_b32 m0, s31
	s_nop 0
	global_load_lds_dwordx4 v[162:163], off
	v_lshl_add_u64 v[162:163], v[214:215], 0, s[46:47]
	s_mov_b32 m0, s37
	s_nop 0
	global_load_lds_dwordx4 v[162:163], off
	s_waitcnt vmcnt(8)
	s_waitcnt lgkmcnt(0)
	s_setprio 1
	s_barrier
	v_mfma_f32_16x16x32_bf16 v[64:67], v[134:137], v[176:179], v[64:67]
	v_mfma_f32_16x16x32_bf16 v[48:51], v[134:137], v[186:189], v[48:51]
	v_mfma_f32_16x16x32_bf16 v[32:35], v[134:137], v[194:197], v[32:35]
	v_mfma_f32_16x16x32_bf16 v[16:19], v[134:137], v[202:205], v[16:19]
	v_mfma_f32_16x16x32_bf16 v[60:63], v[142:145], v[176:179], v[60:63]
	v_mfma_f32_16x16x32_bf16 v[44:47], v[142:145], v[186:189], v[44:47]
	v_mfma_f32_16x16x32_bf16 v[28:31], v[142:145], v[194:197], v[28:31]
	v_mfma_f32_16x16x32_bf16 v[12:15], v[142:145], v[202:205], v[12:15]
	v_mfma_f32_16x16x32_bf16 v[64:67], v[138:141], v[180:183], v[64:67]
	v_mfma_f32_16x16x32_bf16 v[48:51], v[138:141], v[190:193], v[48:51]
	v_mfma_f32_16x16x32_bf16 v[32:35], v[138:141], v[198:201], v[32:35]
	v_mfma_f32_16x16x32_bf16 v[16:19], v[138:141], v[206:209], v[16:19]
	v_mfma_f32_16x16x32_bf16 v[60:63], v[146:149], v[180:183], v[60:63]
	v_mfma_f32_16x16x32_bf16 v[44:47], v[146:149], v[190:193], v[44:47]
	v_mfma_f32_16x16x32_bf16 v[28:31], v[146:149], v[198:201], v[28:31]
	v_mfma_f32_16x16x32_bf16 v[12:15], v[146:149], v[206:209], v[12:15]
	s_setprio 0
	s_setprio 1
	v_mfma_f32_16x16x32_bf16 v[56:59], v[150:153], v[176:179], v[56:59]
	v_mfma_f32_16x16x32_bf16 v[40:43], v[150:153], v[186:189], v[40:43]
	v_mfma_f32_16x16x32_bf16 v[24:27], v[150:153], v[194:197], v[24:27]
	v_mfma_f32_16x16x32_bf16 v[8:11], v[150:153], v[202:205], v[8:11]
	v_mfma_f32_16x16x32_bf16 v[52:55], v[158:161], v[176:179], v[52:55]
	v_mfma_f32_16x16x32_bf16 v[36:39], v[158:161], v[186:189], v[36:39]
	v_mfma_f32_16x16x32_bf16 v[20:23], v[158:161], v[194:197], v[20:23]
	v_mfma_f32_16x16x32_bf16 v[4:7], v[158:161], v[202:205], v[4:7]
	v_mfma_f32_16x16x32_bf16 v[56:59], v[154:157], v[180:183], v[56:59]
	v_mfma_f32_16x16x32_bf16 v[40:43], v[154:157], v[190:193], v[40:43]
	v_mfma_f32_16x16x32_bf16 v[24:27], v[154:157], v[198:201], v[24:27]
	v_mfma_f32_16x16x32_bf16 v[8:11], v[154:157], v[206:209], v[8:11]
	v_mfma_f32_16x16x32_bf16 v[52:55], v[172:175], v[180:183], v[52:55]
	v_mfma_f32_16x16x32_bf16 v[36:39], v[172:175], v[190:193], v[36:39]
	v_mfma_f32_16x16x32_bf16 v[20:23], v[172:175], v[198:201], v[20:23]
	v_mfma_f32_16x16x32_bf16 v[4:7], v[172:175], v[206:209], v[4:7]
	s_setprio 0
	s_barrier
	s_add_i32 s75, s75, 2
	s_add_u32 s55, s55, 0x100
	s_addc_u32 s74, s74, 0
	s_cmpk_gt_u32 s75, 0x55
	s_mov_b64 s[16:17], s[18:19]
	s_cbranch_scc1 .LBB0_45

; #define PG8_STAGE(bufoff, gbase, voff) do { _Pragma("unroll") for (int _i = 0; _i < 2; ++_i) \
;         __builtin_amdgcn_global_load_lds((const unsigned*)((const char*)(gbase) + (voff)[_i]), (PG8_LAS unsigned*)(lds + (bufoff) + ldsw + _i * 8192), 16, 0, 0); } while (0)
; #define PG8_LDA(dst, b, h) do { _Pragma("unroll") for (int m = 0; m < 4; ++m) _Pragma("unroll") for (int k = 0; k < 2; ++k) dst[m][k] = *(const PG8_LAS bf16x8*)(lds + PG8_SA(b, h) + aoff + m * 2048 + k * 1024); } while (0)
; #define PG8_LDB(dst, b, h) do { _Pragma("unroll") for (int n = 0; n < 2; ++n) _Pragma("unroll") for (int k = 0; k < 2; ++k) dst[n][k] = *(const PG8_LAS bf16x8*)(lds + PG8_SB(b, h) + boff + n * 2048 + k * 1024); } while (0)
; #define PG8_MMA(ai, bj, At, Bt) do { __builtin_amdgcn_s_setprio(1); _Pragma("unroll") for (int m = 0; m < 4; ++m) _Pragma("unroll") for (int n = 0; n < 2; ++n) _Pragma("unroll") for (int k = 0; k < 2; ++k) \
;         acc[ai][bj][m][n] = __builtin_amdgcn_mfma_f32_16x16x32_bf16(Bt[n][k], At[m][k], acc[ai][bj][m][n], 0, 0, 0); __builtin_amdgcn_s_setprio(0); } while (0)
; #define PG8_WAIT_V(n) asm volatile("s_waitcnt vmcnt(" #n ")" ::: "memory")
; #define PG8_WAIT_L(n) asm volatile("s_waitcnt lgkmcnt(" #n ")" ::: "memory")
; #define PG8_BAR __builtin_amdgcn_s_barrier()
; #define PG8_SCHED __builtin_amdgcn_sched_barrier(0)
; template <class Epi, class Sched, bool ALIGN_EPI = false, bool SP2 = false>
; __device__ __forceinline__ void gemm_phase(PG8_LAS unsigned char* lds, const Gemm g, const Sched& S, const Epi& E, const int tid) {
;     ...
;             const char* a1 = cA + (size_t)(t + 1) * kstep;
;             const char* a2 = last ? nA : cA + (size_t)(t + 2) * kstep; const char* b2 = last ? nB : cB + (size_t)(t + 2) * kstep;
;             const char* a3 = a2 + kstep; const char* b3 = b2 + kstep;
;             if (last && has_next) S.a_ready(nxt);
;             if (last) E.prefetch(lds + EPI_LDS_OFF + wid * 1024, cur, wr, wc, lane);
;             if constexpr (SP2) {
;             PG8_LDB(B0, 0, 0); PG8_LDB(B1, 0, 1); PG8_SCHED; PG8_LDA(At, 0, 0); PG8_STAGE(PG8_SA(1, 1), a1 + hstep, voffA);
;             PG8_WAIT_V(8); PG8_WAIT_L(0); PG8_BAR; PG8_MMA(0, 0, At, B0); PG8_MMA(0, 1, At, B1); PG8_BAR; PG8_SCHED;
;             PG8_LDA(At, 0, 1); PG8_STAGE(PG8_SB(0, 0), b2, voffB); PG8_STAGE(PG8_SB(0, 1), b2 + hstep, voffB); PG8_STAGE(PG8_SA(0, 0), a2, voffA);
.LBB0_74:
	s_add_u32 s30, s24, 0xfff80080
	s_addc_u32 s31, s25, -1
	s_and_b64 s[28:29], s[28:29], exec
	s_cselect_b32 s31, s17, s31
	s_cselect_b32 s30, s23, s30
	s_cselect_b32 s29, s99, s50
	s_cselect_b32 s28, vcc_lo, vcc_hi
	s_add_i32 s42, 0, 0x10000
	v_add_u32_e32 v110, s42, v247
	s_add_i32 s3, 0, 0x14000
	ds_read_b128 v[98:101], v110
	ds_read_b128 v[102:105], v110 offset:1024
	ds_read_b128 v[106:109], v110 offset:2048
	ds_read_b128 v[144:147], v110 offset:3072
	v_add_u32_e32 v110, s3, v247
	ds_read_b128 v[152:155], v110
	ds_read_b128 v[156:159], v110 offset:1024
	ds_read_b128 v[160:163], v110 offset:2048
	ds_read_b128 v[164:167], v110 offset:3072
	v_lshl_add_u64 v[110:111], s[24:25], 0, v[190:191]
	s_add_i32 m0, s49, 0xc000
	ds_read_b128 v[168:171], v253
	ds_read_b128 v[172:175], v253 offset:1024
	ds_read_b128 v[176:179], v253 offset:2048
	ds_read_b128 v[194:197], v253 offset:3072
	ds_read_b128 v[198:201], v253 offset:4096
	ds_read_b128 v[202:205], v253 offset:5120
	ds_read_b128 v[206:209], v253 offset:6144
	ds_read_b128 v[210:213], v253 offset:7168
	global_load_lds_dwordx4 v[110:111], off
	v_lshl_add_u64 v[110:111], s[24:25], 0, v[192:193]
	s_add_i32 m0, s49, 0xe000
	s_nop 0
	global_load_lds_dwordx4 v[110:111], off
	s_waitcnt vmcnt(8)
	s_waitcnt lgkmcnt(0)
	s_setprio 1
	s_barrier
	v_mfma_f32_16x16x32_bf16 v[148:151], v[98:101], v[168:171], v[148:151]
	v_mfma_f32_16x16x32_bf16 v[128:131], v[98:101], v[176:179], v[128:131]
	v_mfma_f32_16x16x32_bf16 v[110:113], v[98:101], v[198:201], v[112:115]
	v_mfma_f32_16x16x32_bf16 v[80:83], v[98:101], v[206:209], v[80:83]
	v_mfma_f32_16x16x32_bf16 v[140:143], v[106:109], v[168:171], v[140:143]
	v_mfma_f32_16x16x32_bf16 v[124:127], v[106:109], v[176:179], v[124:127]
	v_mfma_f32_16x16x32_bf16 v[92:95], v[106:109], v[198:201], v[92:95]
	v_mfma_f32_16x16x32_bf16 v[76:79], v[106:109], v[206:209], v[76:79]
	v_mfma_f32_16x16x32_bf16 v[148:151], v[102:105], v[172:175], v[148:151]
	v_mfma_f32_16x16x32_bf16 v[128:131], v[102:105], v[194:197], v[128:131]
	v_mfma_f32_16x16x32_bf16 v[110:113], v[102:105], v[202:205], v[110:113]
	v_mfma_f32_16x16x32_bf16 v[80:83], v[102:105], v[210:213], v[80:83]
	v_mfma_f32_16x16x32_bf16 v[140:143], v[144:147], v[172:175], v[140:143]
	v_mfma_f32_16x16x32_bf16 v[124:127], v[144:147], v[194:197], v[124:127]
	v_mfma_f32_16x16x32_bf16 v[92:95], v[144:147], v[202:205], v[92:95]
	v_mfma_f32_16x16x32_bf16 v[76:79], v[144:147], v[210:213], v[76:79]
	s_setprio 0
	s_setprio 1
	v_mfma_f32_16x16x32_bf16 v[136:139], v[152:155], v[168:171], v[136:139]
	v_mfma_f32_16x16x32_bf16 v[120:123], v[152:155], v[176:179], v[120:123]
	v_mfma_f32_16x16x32_bf16 v[88:91], v[152:155], v[198:201], v[88:91]
	v_mfma_f32_16x16x32_bf16 v[72:75], v[152:155], v[206:209], v[72:75]
	v_mfma_f32_16x16x32_bf16 v[132:135], v[160:163], v[168:171], v[132:135]
	v_mfma_f32_16x16x32_bf16 v[114:117], v[160:163], v[176:179], v[116:119]
	v_mfma_f32_16x16x32_bf16 v[84:87], v[160:163], v[198:201], v[84:87]
	v_mfma_f32_16x16x32_bf16 v[68:71], v[160:163], v[206:209], v[68:71]
	v_mfma_f32_16x16x32_bf16 v[136:139], v[156:159], v[172:175], v[136:139]
	v_mfma_f32_16x16x32_bf16 v[120:123], v[156:159], v[194:197], v[120:123]
	v_mfma_f32_16x16x32_bf16 v[88:91], v[156:159], v[202:205], v[88:91]
	v_mfma_f32_16x16x32_bf16 v[72:75], v[156:159], v[210:213], v[72:75]
	v_mfma_f32_16x16x32_bf16 v[132:135], v[164:167], v[172:175], v[132:135]
	v_mfma_f32_16x16x32_bf16 v[116:119], v[164:167], v[194:197], v[114:117]
	v_mfma_f32_16x16x32_bf16 v[84:87], v[164:167], v[202:205], v[84:87]
	v_mfma_f32_16x16x32_bf16 v[68:71], v[164:167], v[210:213], v[68:71]
	s_setprio 0
	s_barrier
	s_add_i32 s42, s42, s48
	v_lshl_add_u64 v[180:181], s[28:29], 0, v[2:3]
	s_mov_b32 m0, s42
	ds_read_b128 v[168:171], v253 offset:16384
	ds_read_b128 v[172:175], v253 offset:17408
	ds_read_b128 v[176:179], v253 offset:18432
	ds_read_b128 v[194:197], v253 offset:19456
	ds_read_b128 v[198:201], v253 offset:20480
	ds_read_b128 v[202:205], v253 offset:21504
	ds_read_b128 v[206:209], v253 offset:22528
	ds_read_b128 v[210:213], v253 offset:23552
	global_load_lds_dwordx4 v[180:181], off
	s_add_i32 m0, s42, 0x2000
	s_add_u32 s42, s28, 0x80000
	v_lshl_add_u64 v[182:183], s[28:29], 0, v[188:189]
	s_addc_u32 s43, s29, 0
	s_add_i32 s3, s3, s48
	global_load_lds_dwordx4 v[182:183], off
	v_lshl_add_u64 v[114:115], s[42:43], 0, v[2:3]
	s_mov_b32 m0, s3
	v_lshl_add_u64 v[214:215], s[30:31], 0, v[0:1]
	global_load_lds_dwordx4 v[114:115], off
	v_lshl_add_u64 v[114:115], s[42:43], 0, v[188:189]
	s_add_i32 m0, s3, 0x2000
	v_lshl_add_u64 v[216:217], s[30:31], 0, v[186:187]
	global_load_lds_dwordx4 v[114:115], off
	s_mov_b32 m0, s49
	s_nop 0
	global_load_lds_dwordx4 v[214:215], off
	s_mov_b32 m0, s52
	s_nop 0
	global_load_lds_dwordx4 v[216:217], off
	s_waitcnt vmcnt(8)
	s_waitcnt lgkmcnt(0)
	s_setprio 1
	s_barrier
; #define PG8_STAGE(bufoff, gbase, voff) do { _Pragma("unroll") for (int _i = 0; _i < 2; ++_i) \
;         __builtin_amdgcn_global_load_lds((const unsigned*)((const char*)(gbase) + (voff)[_i]), (PG8_LAS unsigned*)(lds + (bufoff) + ldsw + _i * 8192), 16, 0, 0); } while (0)
; #define PG8_LDA(dst, b, h) do { _Pragma("unroll") for (int m = 0; m < 4; ++m) _Pragma("unroll") for (int k = 0; k < 2; ++k) dst[m][k] = *(const PG8_LAS bf16x8*)(lds + PG8_SA(b, h) + aoff + m * 2048 + k * 1024); } while (0)
; #define PG8_LDB(dst, b, h) do { _Pragma("unroll") for (int n = 0; n < 2; ++n) _Pragma("unroll") for (int k = 0; k < 2; ++k) dst[n][k] = *(const PG8_LAS bf16x8*)(lds + PG8_SB(b, h) + boff + n * 2048 + k * 1024); } while (0)
; #define PG8_MMA(ai, bj, At, Bt) do { __builtin_amdgcn_s_setprio(1); _Pragma("unroll") for (int m = 0; m < 4; ++m) _Pragma("unroll") for (int n = 0; n < 2; ++n) _Pragma("unroll") for (int k = 0; k < 2; ++k) \
;         acc[ai][bj][m][n] = __builtin_amdgcn_mfma_f32_16x16x32_bf16(Bt[n][k], At[m][k], acc[ai][bj][m][n], 0, 0, 0); __builtin_amdgcn_s_setprio(0); } while (0)
; #define PG8_WAIT_V(n) asm volatile("s_waitcnt vmcnt(" #n ")" ::: "memory")
; #define PG8_WAIT_L(n) asm volatile("s_waitcnt lgkmcnt(" #n ")" ::: "memory")
; #define PG8_BAR __builtin_amdgcn_s_barrier()
; #define PG8_SCHED __builtin_amdgcn_sched_barrier(0)
; template <class Epi, class Sched, bool ALIGN_EPI = false, bool SP2 = false>
; __device__ __forceinline__ void gemm_phase(PG8_LAS unsigned char* lds, const Gemm g, const Sched& S, const Epi& E, const int tid) {
;     ...
;             PG8_WAIT_V(8); PG8_WAIT_L(0); PG8_BAR; PG8_MMA(1, 0, At, B0); PG8_MMA(1, 1, At, B1); PG8_BAR; PG8_SCHED;
;             PG8_LDB(B0, 1, 0); PG8_LDB(B1, 1, 1); PG8_SCHED; PG8_LDA(At, 1, 0); PG8_STAGE(PG8_SA(0, 1), a2 + hstep, voffA);
;             PG8_WAIT_V(8); PG8_WAIT_L(0); PG8_BAR; PG8_MMA(0, 0, At, B0); PG8_MMA(0, 1, At, B1); PG8_BAR; PG8_SCHED;
	v_mfma_f32_16x16x32_bf16 v[64:67], v[98:101], v[168:171], v[64:67]
	v_mfma_f32_16x16x32_bf16 v[48:51], v[98:101], v[176:179], v[48:51]
	v_mfma_f32_16x16x32_bf16 v[32:35], v[98:101], v[198:201], v[32:35]
	v_mfma_f32_16x16x32_bf16 v[16:19], v[98:101], v[206:209], v[16:19]
	v_mfma_f32_16x16x32_bf16 v[60:63], v[106:109], v[168:171], v[60:63]
	v_mfma_f32_16x16x32_bf16 v[44:47], v[106:109], v[176:179], v[44:47]
	v_mfma_f32_16x16x32_bf16 v[28:31], v[106:109], v[198:201], v[28:31]
	v_mfma_f32_16x16x32_bf16 v[12:15], v[106:109], v[206:209], v[12:15]
	v_mfma_f32_16x16x32_bf16 v[64:67], v[102:105], v[172:175], v[64:67]
	v_mfma_f32_16x16x32_bf16 v[48:51], v[102:105], v[194:197], v[48:51]
	v_mfma_f32_16x16x32_bf16 v[32:35], v[102:105], v[202:205], v[32:35]
	v_mfma_f32_16x16x32_bf16 v[16:19], v[102:105], v[210:213], v[16:19]
	v_mfma_f32_16x16x32_bf16 v[60:63], v[144:147], v[172:175], v[60:63]
	v_mfma_f32_16x16x32_bf16 v[44:47], v[144:147], v[194:197], v[44:47]
	v_mfma_f32_16x16x32_bf16 v[28:31], v[144:147], v[202:205], v[28:31]
	v_mfma_f32_16x16x32_bf16 v[12:15], v[144:147], v[210:213], v[12:15]
	s_setprio 0
	s_setprio 1
	v_mfma_f32_16x16x32_bf16 v[56:59], v[152:155], v[168:171], v[56:59]
	v_mfma_f32_16x16x32_bf16 v[40:43], v[152:155], v[176:179], v[40:43]
	v_mfma_f32_16x16x32_bf16 v[24:27], v[152:155], v[198:201], v[24:27]
	v_mfma_f32_16x16x32_bf16 v[8:11], v[152:155], v[206:209], v[8:11]
	v_mfma_f32_16x16x32_bf16 v[52:55], v[160:163], v[168:171], v[52:55]
	v_mfma_f32_16x16x32_bf16 v[36:39], v[160:163], v[176:179], v[36:39]
	v_mfma_f32_16x16x32_bf16 v[20:23], v[160:163], v[198:201], v[20:23]
	v_mfma_f32_16x16x32_bf16 v[4:7], v[160:163], v[206:209], v[4:7]
	v_mfma_f32_16x16x32_bf16 v[56:59], v[156:159], v[172:175], v[56:59]
	v_mfma_f32_16x16x32_bf16 v[40:43], v[156:159], v[194:197], v[40:43]
	v_mfma_f32_16x16x32_bf16 v[24:27], v[156:159], v[202:205], v[24:27]
	v_mfma_f32_16x16x32_bf16 v[8:11], v[156:159], v[210:213], v[8:11]
	v_mfma_f32_16x16x32_bf16 v[52:55], v[164:167], v[172:175], v[52:55]
	v_mfma_f32_16x16x32_bf16 v[36:39], v[164:167], v[194:197], v[36:39]
	v_mfma_f32_16x16x32_bf16 v[20:23], v[164:167], v[202:205], v[20:23]
	v_mfma_f32_16x16x32_bf16 v[4:7], v[164:167], v[210:213], v[4:7]
	s_setprio 0
	s_barrier
	s_add_i32 s3, 0, 0x18000
	v_add_u32_e32 v114, s3, v247
	s_add_i32 s42, 0, 0x1c000
	ds_read_b128 v[98:101], v114
	ds_read_b128 v[102:105], v114 offset:1024
	ds_read_b128 v[106:109], v114 offset:2048
	ds_read_b128 v[144:147], v114 offset:3072
	v_add_u32_e32 v114, s42, v247
	ds_read_b128 v[152:155], v114
	ds_read_b128 v[156:159], v114 offset:1024
	ds_read_b128 v[160:163], v114 offset:2048
	ds_read_b128 v[164:167], v114 offset:3072
	s_add_u32 s30, s30, 0x80000
	s_addc_u32 s31, s31, 0
	s_mov_b32 m0, s53
	v_lshl_add_u64 v[114:115], s[30:31], 0, v[0:1]
	ds_read_b128 v[168:171], v253 offset:32768
	ds_read_b128 v[172:175], v253 offset:33792
	ds_read_b128 v[176:179], v253 offset:34816
	ds_read_b128 v[194:197], v253 offset:35840
	ds_read_b128 v[198:201], v253 offset:36864
	ds_read_b128 v[202:205], v253 offset:37888
	ds_read_b128 v[206:209], v253 offset:38912
	ds_read_b128 v[210:213], v253 offset:39936
	global_load_lds_dwordx4 v[114:115], off
	v_lshl_add_u64 v[114:115], s[30:31], 0, v[186:187]
	s_mov_b32 m0, s54
	s_nop 0
	global_load_lds_dwordx4 v[114:115], off
	s_waitcnt vmcnt(8)
	s_waitcnt lgkmcnt(0)
	s_setprio 1
	s_barrier
	v_mfma_f32_16x16x32_bf16 v[148:151], v[98:101], v[168:171], v[148:151]
	v_mfma_f32_16x16x32_bf16 v[128:131], v[98:101], v[176:179], v[128:131]
	v_mfma_f32_16x16x32_bf16 v[110:113], v[98:101], v[198:201], v[110:113]
	v_mfma_f32_16x16x32_bf16 v[80:83], v[98:101], v[206:209], v[80:83]
	v_mfma_f32_16x16x32_bf16 v[140:143], v[106:109], v[168:171], v[140:143]
	v_mfma_f32_16x16x32_bf16 v[124:127], v[106:109], v[176:179], v[124:127]
	v_mfma_f32_16x16x32_bf16 v[92:95], v[106:109], v[198:201], v[92:95]
	v_mfma_f32_16x16x32_bf16 v[76:79], v[106:109], v[206:209], v[76:79]
	v_mfma_f32_16x16x32_bf16 v[148:151], v[102:105], v[172:175], v[148:151]
	v_mfma_f32_16x16x32_bf16 v[128:131], v[102:105], v[194:197], v[128:131]
	v_mfma_f32_16x16x32_bf16 v[112:115], v[102:105], v[202:205], v[110:113]
	v_mfma_f32_16x16x32_bf16 v[80:83], v[102:105], v[210:213], v[80:83]
	v_mfma_f32_16x16x32_bf16 v[140:143], v[144:147], v[172:175], v[140:143]
	v_mfma_f32_16x16x32_bf16 v[124:127], v[144:147], v[194:197], v[124:127]
	v_mfma_f32_16x16x32_bf16 v[92:95], v[144:147], v[202:205], v[92:95]
	v_mfma_f32_16x16x32_bf16 v[76:79], v[144:147], v[210:213], v[76:79]
	s_setprio 0
	s_setprio 1
	v_mfma_f32_16x16x32_bf16 v[136:139], v[152:155], v[168:171], v[136:139]
	v_mfma_f32_16x16x32_bf16 v[120:123], v[152:155], v[176:179], v[120:123]
	v_mfma_f32_16x16x32_bf16 v[88:91], v[152:155], v[198:201], v[88:91]
	v_mfma_f32_16x16x32_bf16 v[72:75], v[152:155], v[206:209], v[72:75]
	v_mfma_f32_16x16x32_bf16 v[132:135], v[160:163], v[168:171], v[132:135]
	v_mfma_f32_16x16x32_bf16 v[116:119], v[160:163], v[176:179], v[116:119]
	v_mfma_f32_16x16x32_bf16 v[84:87], v[160:163], v[198:201], v[84:87]
	v_mfma_f32_16x16x32_bf16 v[68:71], v[160:163], v[206:209], v[68:71]
	v_mfma_f32_16x16x32_bf16 v[136:139], v[156:159], v[172:175], v[136:139]
	v_mfma_f32_16x16x32_bf16 v[120:123], v[156:159], v[194:197], v[120:123]
	v_mfma_f32_16x16x32_bf16 v[88:91], v[156:159], v[202:205], v[88:91]
	v_mfma_f32_16x16x32_bf16 v[72:75], v[156:159], v[210:213], v[72:75]
	v_mfma_f32_16x16x32_bf16 v[132:135], v[164:167], v[172:175], v[132:135]
	v_mfma_f32_16x16x32_bf16 v[116:119], v[164:167], v[194:197], v[116:119]
	v_mfma_f32_16x16x32_bf16 v[84:87], v[164:167], v[202:205], v[84:87]
	v_mfma_f32_16x16x32_bf16 v[68:71], v[164:167], v[210:213], v[68:71]
	s_setprio 0
	s_barrier
; #define PG8_STAGE(bufoff, gbase, voff) do { _Pragma("unroll") for (int _i = 0; _i < 2; ++_i) \
;         __builtin_amdgcn_global_load_lds((const unsigned*)((const char*)(gbase) + (voff)[_i]), (PG8_LAS unsigned*)(lds + (bufoff) + ldsw + _i * 8192), 16, 0, 0); } while (0)
; #define PG8_LDA(dst, b, h) do { _Pragma("unroll") for (int m = 0; m < 4; ++m) _Pragma("unroll") for (int k = 0; k < 2; ++k) dst[m][k] = *(const PG8_LAS bf16x8*)(lds + PG8_SA(b, h) + aoff + m * 2048 + k * 1024); } while (0)
; #define PG8_MMA(ai, bj, At, Bt) do { __builtin_amdgcn_s_setprio(1); _Pragma("unroll") for (int m = 0; m < 4; ++m) _Pragma("unroll") for (int n = 0; n < 2; ++n) _Pragma("unroll") for (int k = 0; k < 2; ++k) \
;         acc[ai][bj][m][n] = __builtin_amdgcn_mfma_f32_16x16x32_bf16(Bt[n][k], At[m][k], acc[ai][bj][m][n], 0, 0, 0); __builtin_amdgcn_s_setprio(0); } while (0)
; #define PG8_WAIT_V(n) asm volatile("s_waitcnt vmcnt(" #n ")" ::: "memory")
; #define PG8_WAIT_L(n) asm volatile("s_waitcnt lgkmcnt(" #n ")" ::: "memory")
; #define PG8_BAR __builtin_amdgcn_s_barrier()
; #define PG8_SCHED __builtin_amdgcn_sched_barrier(0)
; template <class Epi, class Sched, bool ALIGN_EPI = false, bool SP2 = false>
; __device__ __forceinline__ void gemm_phase(PG8_LAS unsigned char* lds, const Gemm g, const Sched& S, const Epi& E, const int tid) {
;     ...
;             PG8_LDA(At, 1, 1); PG8_STAGE(PG8_SB(1, 0), b3, voffB); PG8_STAGE(PG8_SB(1, 1), b3 + hstep, voffB); PG8_STAGE(PG8_SA(1, 0), a3, voffA);
;             PG8_WAIT_V(8); PG8_WAIT_L(0); PG8_BAR; PG8_MMA(1, 0, At, B0); PG8_MMA(1, 1, At, B1); PG8_BAR; PG8_SCHED;
	s_add_i32 s3, s3, s48
	v_lshl_add_u64 v[110:111], v[180:181], 0, s[46:47]
	s_mov_b32 m0, s3
	ds_read_b128 v[168:171], v253 offset:49152
	ds_read_b128 v[172:175], v253 offset:50176
	ds_read_b128 v[176:179], v253 offset:51200
	ds_read_b128 v[194:197], v253 offset:52224
	ds_read_b128 v[198:201], v253 offset:53248
	ds_read_b128 v[202:205], v253 offset:54272
	ds_read_b128 v[206:209], v253 offset:55296
	ds_read_b128 v[210:213], v253 offset:56320
	global_load_lds_dwordx4 v[110:111], off
	s_add_i32 m0, s3, 0x2000
	s_add_u32 s28, s28, 0x80080
	v_lshl_add_u64 v[110:111], v[182:183], 0, s[46:47]
	s_addc_u32 s29, s29, 0
	s_add_i32 s3, s42, s48
	global_load_lds_dwordx4 v[110:111], off
	v_lshl_add_u64 v[110:111], s[28:29], 0, v[2:3]
	s_mov_b32 m0, s3
	s_nop 0
	global_load_lds_dwordx4 v[110:111], off
	v_lshl_add_u64 v[110:111], s[28:29], 0, v[188:189]
	s_add_i32 m0, s3, 0x2000
	s_nop 0
	global_load_lds_dwordx4 v[110:111], off
	v_lshl_add_u64 v[110:111], v[214:215], 0, s[46:47]
	s_mov_b32 m0, s55
	s_nop 0
	global_load_lds_dwordx4 v[110:111], off
	v_lshl_add_u64 v[110:111], v[216:217], 0, s[46:47]
	s_mov_b32 m0, s74
	s_nop 0
	global_load_lds_dwordx4 v[110:111], off
	s_waitcnt vmcnt(8)
	s_waitcnt lgkmcnt(0)
	s_setprio 1
	s_barrier
	v_mfma_f32_16x16x32_bf16 v[64:67], v[98:101], v[168:171], v[64:67]
	v_mfma_f32_16x16x32_bf16 v[48:51], v[98:101], v[176:179], v[48:51]
	v_mfma_f32_16x16x32_bf16 v[32:35], v[98:101], v[198:201], v[32:35]
	v_mfma_f32_16x16x32_bf16 v[16:19], v[98:101], v[206:209], v[16:19]
	v_mfma_f32_16x16x32_bf16 v[60:63], v[106:109], v[168:171], v[60:63]
	v_mfma_f32_16x16x32_bf16 v[44:47], v[106:109], v[176:179], v[44:47]
	v_mfma_f32_16x16x32_bf16 v[28:31], v[106:109], v[198:201], v[28:31]
	v_mfma_f32_16x16x32_bf16 v[12:15], v[106:109], v[206:209], v[12:15]
	v_mfma_f32_16x16x32_bf16 v[64:67], v[102:105], v[172:175], v[64:67]
	v_mfma_f32_16x16x32_bf16 v[48:51], v[102:105], v[194:197], v[48:51]
	v_mfma_f32_16x16x32_bf16 v[32:35], v[102:105], v[202:205], v[32:35]
	v_mfma_f32_16x16x32_bf16 v[16:19], v[102:105], v[210:213], v[16:19]
	v_mfma_f32_16x16x32_bf16 v[60:63], v[144:147], v[172:175], v[60:63]
	v_mfma_f32_16x16x32_bf16 v[44:47], v[144:147], v[194:197], v[44:47]
	v_mfma_f32_16x16x32_bf16 v[28:31], v[144:147], v[202:205], v[28:31]
	v_mfma_f32_16x16x32_bf16 v[12:15], v[144:147], v[210:213], v[12:15]
	s_setprio 0
	s_setprio 1
	v_mfma_f32_16x16x32_bf16 v[56:59], v[152:155], v[168:171], v[56:59]
	v_mfma_f32_16x16x32_bf16 v[40:43], v[152:155], v[176:179], v[40:43]
	v_mfma_f32_16x16x32_bf16 v[24:27], v[152:155], v[198:201], v[24:27]
	v_mfma_f32_16x16x32_bf16 v[8:11], v[152:155], v[206:209], v[8:11]
	v_mfma_f32_16x16x32_bf16 v[52:55], v[160:163], v[168:171], v[52:55]
	v_mfma_f32_16x16x32_bf16 v[36:39], v[160:163], v[176:179], v[36:39]
	v_mfma_f32_16x16x32_bf16 v[20:23], v[160:163], v[198:201], v[20:23]
	v_mfma_f32_16x16x32_bf16 v[4:7], v[160:163], v[206:209], v[4:7]
	v_mfma_f32_16x16x32_bf16 v[56:59], v[156:159], v[172:175], v[56:59]
	v_mfma_f32_16x16x32_bf16 v[40:43], v[156:159], v[194:197], v[40:43]
	v_mfma_f32_16x16x32_bf16 v[24:27], v[156:159], v[202:205], v[24:27]
	v_mfma_f32_16x16x32_bf16 v[8:11], v[156:159], v[210:213], v[8:11]
	v_mfma_f32_16x16x32_bf16 v[52:55], v[164:167], v[172:175], v[52:55]
	v_mfma_f32_16x16x32_bf16 v[36:39], v[164:167], v[194:197], v[36:39]
	v_mfma_f32_16x16x32_bf16 v[20:23], v[164:167], v[202:205], v[20:23]
	v_mfma_f32_16x16x32_bf16 v[4:7], v[164:167], v[210:213], v[4:7]
	s_setprio 0
	s_barrier
	s_add_i32 s51, s51, 2
	s_add_u32 s24, s24, 0x100
	s_addc_u32 s25, s25, 0
	s_add_u32 vcc_hi, vcc_hi, 0x100
	s_addc_u32 s50, s50, 0
	s_cmp_gt_u32 s51, 29
	s_cbranch_scc1 .LBB0_77

; #define PG8_STAGE(bufoff, gbase, voff) do { _Pragma("unroll") for (int _i = 0; _i < 2; ++_i) \
;         __builtin_amdgcn_global_load_lds((const unsigned*)((const char*)(gbase) + (voff)[_i]), (PG8_LAS unsigned*)(lds + (bufoff) + ldsw + _i * 8192), 16, 0, 0); } while (0)
; #define PG8_LDA(dst, b, h) do { _Pragma("unroll") for (int m = 0; m < 4; ++m) _Pragma("unroll") for (int k = 0; k < 2; ++k) dst[m][k] = *(const PG8_LAS bf16x8*)(lds + PG8_SA(b, h) + aoff + m * 2048 + k * 1024); } while (0)
; #define PG8_LDB(dst, b, h) do { _Pragma("unroll") for (int n = 0; n < 2; ++n) _Pragma("unroll") for (int k = 0; k < 2; ++k) dst[n][k] = *(const PG8_LAS bf16x8*)(lds + PG8_SB(b, h) + boff + n * 2048 + k * 1024); } while (0)
; #define PG8_MMA(ai, bj, At, Bt) do { __builtin_amdgcn_s_setprio(1); _Pragma("unroll") for (int m = 0; m < 4; ++m) _Pragma("unroll") for (int n = 0; n < 2; ++n) _Pragma("unroll") for (int k = 0; k < 2; ++k) \
;         acc[ai][bj][m][n] = __builtin_amdgcn_mfma_f32_16x16x32_bf16(Bt[n][k], At[m][k], acc[ai][bj][m][n], 0, 0, 0); __builtin_amdgcn_s_setprio(0); } while (0)
; #define PG8_WAIT_V(n) asm volatile("s_waitcnt vmcnt(" #n ")" ::: "memory")
; #define PG8_WAIT_L(n) asm volatile("s_waitcnt lgkmcnt(" #n ")" ::: "memory")
; #define PG8_BAR __builtin_amdgcn_s_barrier()
; #define PG8_SCHED __builtin_amdgcn_sched_barrier(0)
; template <class Epi, class Sched, bool ALIGN_EPI = false, bool SP2 = false>
; __device__ __forceinline__ void gemm_phase(PG8_LAS unsigned char* lds, const Gemm g, const Sched& S, const Epi& E, const int tid) {
;     ...
;             const char* a1 = cA + (size_t)(t + 1) * kstep;
;             const char* a2 = last ? nA : cA + (size_t)(t + 2) * kstep; const char* b2 = last ? nB : cB + (size_t)(t + 2) * kstep;
;             const char* a3 = a2 + kstep; const char* b3 = b2 + kstep;
;             if (last && has_next) S.a_ready(nxt);
;             if (last) E.prefetch(lds + EPI_LDS_OFF + wid * 1024, cur, wr, wc, lane);
;             if constexpr (SP2) {
;             PG8_LDB(B0, 0, 0); PG8_LDB(B1, 0, 1); PG8_SCHED; PG8_LDA(At, 0, 0); PG8_STAGE(PG8_SA(1, 1), a1 + hstep, voffA);
;             PG8_WAIT_V(8); PG8_WAIT_L(0); PG8_BAR; PG8_MMA(0, 0, At, B0); PG8_MMA(0, 1, At, B1); PG8_BAR; PG8_SCHED;
;             PG8_LDA(At, 0, 1); PG8_STAGE(PG8_SB(0, 0), b2, voffB); PG8_STAGE(PG8_SB(0, 1), b2 + hstep, voffB); PG8_STAGE(PG8_SA(0, 0), a2, voffA);
.LBB0_156:
	s_add_u32 s3, s26, 0xfff80080
	s_addc_u32 s30, s27, -1
	s_and_b64 s[28:29], s[28:29], exec
	s_cselect_b32 s31, s9, s30
	s_cselect_b32 s30, s17, s3
	s_cselect_b32 s29, s15, s25
	s_cselect_b32 s28, s39, s23
	s_add_i32 s3, 0, 0x10000
	v_add_u32_e32 v34, s3, v167
	s_add_i32 s51, 0, 0x14000
	ds_read_b128 v[44:47], v34
	ds_read_b128 v[48:51], v34 offset:1024
	ds_read_b128 v[160:163], v34 offset:2048
	ds_read_b128 v[172:175], v34 offset:3072
	v_add_u32_e32 v34, s51, v167
	ds_read_b128 v[176:179], v34
	ds_read_b128 v[180:183], v34 offset:1024
	ds_read_b128 v[186:189], v34 offset:2048
	ds_read_b128 v[190:193], v34 offset:3072
	v_lshl_add_u64 v[34:35], s[26:27], 0, v[156:157]
	s_add_i32 m0, s48, 0xc000
	ds_read_b128 v[194:197], v171
	ds_read_b128 v[198:201], v171 offset:1024
	ds_read_b128 v[202:205], v171 offset:2048
	ds_read_b128 v[206:209], v171 offset:3072
	ds_read_b128 v[210:213], v171 offset:4096
	ds_read_b128 v[214:217], v171 offset:5120
	ds_read_b128 v[218:221], v171 offset:6144
	ds_read_b128 v[222:225], v171 offset:7168
	global_load_lds_dwordx4 v[34:35], off
	v_lshl_add_u64 v[34:35], s[26:27], 0, v[158:159]
	s_add_i32 m0, s48, 0xe000
	s_nop 0
	global_load_lds_dwordx4 v[34:35], off
	s_waitcnt vmcnt(8)
	s_waitcnt lgkmcnt(0)
	s_setprio 1
	s_barrier
	v_mfma_f32_16x16x32_bf16 v[144:147], v[44:47], v[194:197], v[144:147]
	v_mfma_f32_16x16x32_bf16 v[128:131], v[44:47], v[202:205], v[128:131]
	v_mfma_f32_16x16x32_bf16 v[112:115], v[44:47], v[210:213], v[112:115]
	v_mfma_f32_16x16x32_bf16 v[96:99], v[44:47], v[218:221], v[96:99]
	v_mfma_f32_16x16x32_bf16 v[140:143], v[160:163], v[194:197], v[140:143]
	v_mfma_f32_16x16x32_bf16 v[124:127], v[160:163], v[202:205], v[124:127]
	v_mfma_f32_16x16x32_bf16 v[108:111], v[160:163], v[210:213], v[108:111]
	v_mfma_f32_16x16x32_bf16 v[92:95], v[160:163], v[218:221], v[92:95]
	v_mfma_f32_16x16x32_bf16 v[144:147], v[48:51], v[198:201], v[144:147]
	v_mfma_f32_16x16x32_bf16 v[128:131], v[48:51], v[206:209], v[128:131]
	v_mfma_f32_16x16x32_bf16 v[112:115], v[48:51], v[214:217], v[112:115]
	v_mfma_f32_16x16x32_bf16 v[96:99], v[48:51], v[222:225], v[96:99]
	v_mfma_f32_16x16x32_bf16 v[140:143], v[172:175], v[198:201], v[140:143]
	v_mfma_f32_16x16x32_bf16 v[124:127], v[172:175], v[206:209], v[124:127]
	v_mfma_f32_16x16x32_bf16 v[108:111], v[172:175], v[214:217], v[108:111]
	v_mfma_f32_16x16x32_bf16 v[92:95], v[172:175], v[222:225], v[92:95]
	s_setprio 0
	s_setprio 1
	v_mfma_f32_16x16x32_bf16 v[136:139], v[176:179], v[194:197], v[136:139]
	v_mfma_f32_16x16x32_bf16 v[120:123], v[176:179], v[202:205], v[120:123]
	v_mfma_f32_16x16x32_bf16 v[104:107], v[176:179], v[210:213], v[104:107]
	v_mfma_f32_16x16x32_bf16 v[88:91], v[176:179], v[218:221], v[88:91]
	v_mfma_f32_16x16x32_bf16 v[132:135], v[186:189], v[194:197], v[132:135]
	v_mfma_f32_16x16x32_bf16 v[116:119], v[186:189], v[202:205], v[116:119]
	v_mfma_f32_16x16x32_bf16 v[100:103], v[186:189], v[210:213], v[100:103]
	v_mfma_f32_16x16x32_bf16 v[84:87], v[186:189], v[218:221], v[84:87]
	v_mfma_f32_16x16x32_bf16 v[136:139], v[180:183], v[198:201], v[136:139]
	v_mfma_f32_16x16x32_bf16 v[120:123], v[180:183], v[206:209], v[120:123]
	v_mfma_f32_16x16x32_bf16 v[104:107], v[180:183], v[214:217], v[104:107]
	v_mfma_f32_16x16x32_bf16 v[88:91], v[180:183], v[222:225], v[88:91]
	v_mfma_f32_16x16x32_bf16 v[132:135], v[190:193], v[198:201], v[132:135]
	v_mfma_f32_16x16x32_bf16 v[116:119], v[190:193], v[206:209], v[116:119]
	v_mfma_f32_16x16x32_bf16 v[100:103], v[190:193], v[214:217], v[100:103]
	v_mfma_f32_16x16x32_bf16 v[84:87], v[190:193], v[222:225], v[84:87]
	s_setprio 0
	s_barrier
	s_add_i32 s3, s3, s44
	v_lshl_add_u64 v[164:165], s[28:29], 0, v[2:3]
	s_mov_b32 m0, s3
	ds_read_b128 v[194:197], v171 offset:16384
	ds_read_b128 v[198:201], v171 offset:17408
	ds_read_b128 v[202:205], v171 offset:18432
	ds_read_b128 v[206:209], v171 offset:19456
	ds_read_b128 v[210:213], v171 offset:20480
	ds_read_b128 v[214:217], v171 offset:21504
	ds_read_b128 v[218:221], v171 offset:22528
	ds_read_b128 v[222:225], v171 offset:23552
	global_load_lds_dwordx4 v[164:165], off
	s_add_i32 m0, s3, 0x2000
	s_add_u32 s42, s28, 0x80000
	v_lshl_add_u64 v[226:227], s[28:29], 0, v[150:151]
	s_addc_u32 s43, s29, 0
	s_add_i32 s3, s51, s44
	global_load_lds_dwordx4 v[226:227], off
	v_lshl_add_u64 v[34:35], s[42:43], 0, v[2:3]
	s_mov_b32 m0, s3
	v_lshl_add_u64 v[228:229], s[30:31], 0, v[0:1]
	global_load_lds_dwordx4 v[34:35], off
	v_lshl_add_u64 v[34:35], s[42:43], 0, v[150:151]
	s_add_i32 m0, s3, 0x2000
	v_lshl_add_u64 v[230:231], s[30:31], 0, v[148:149]
	global_load_lds_dwordx4 v[34:35], off
	s_mov_b32 m0, s48
	s_nop 0
	global_load_lds_dwordx4 v[228:229], off
	s_mov_b32 m0, s49
	s_nop 0
	global_load_lds_dwordx4 v[230:231], off
	s_waitcnt vmcnt(8)
	s_waitcnt lgkmcnt(0)
	s_setprio 1
	s_barrier
; #define PG8_STAGE(bufoff, gbase, voff) do { _Pragma("unroll") for (int _i = 0; _i < 2; ++_i) \
;         __builtin_amdgcn_global_load_lds((const unsigned*)((const char*)(gbase) + (voff)[_i]), (PG8_LAS unsigned*)(lds + (bufoff) + ldsw + _i * 8192), 16, 0, 0); } while (0)
; #define PG8_LDA(dst, b, h) do { _Pragma("unroll") for (int m = 0; m < 4; ++m) _Pragma("unroll") for (int k = 0; k < 2; ++k) dst[m][k] = *(const PG8_LAS bf16x8*)(lds + PG8_SA(b, h) + aoff + m * 2048 + k * 1024); } while (0)
; #define PG8_LDB(dst, b, h) do { _Pragma("unroll") for (int n = 0; n < 2; ++n) _Pragma("unroll") for (int k = 0; k < 2; ++k) dst[n][k] = *(const PG8_LAS bf16x8*)(lds + PG8_SB(b, h) + boff + n * 2048 + k * 1024); } while (0)
; #define PG8_MMA(ai, bj, At, Bt) do { __builtin_amdgcn_s_setprio(1); _Pragma("unroll") for (int m = 0; m < 4; ++m) _Pragma("unroll") for (int n = 0; n < 2; ++n) _Pragma("unroll") for (int k = 0; k < 2; ++k) \
;         acc[ai][bj][m][n] = __builtin_amdgcn_mfma_f32_16x16x32_bf16(Bt[n][k], At[m][k], acc[ai][bj][m][n], 0, 0, 0); __builtin_amdgcn_s_setprio(0); } while (0)
; #define PG8_WAIT_V(n) asm volatile("s_waitcnt vmcnt(" #n ")" ::: "memory")
; #define PG8_WAIT_L(n) asm volatile("s_waitcnt lgkmcnt(" #n ")" ::: "memory")
; #define PG8_BAR __builtin_amdgcn_s_barrier()
; #define PG8_SCHED __builtin_amdgcn_sched_barrier(0)
; template <class Epi, class Sched, bool ALIGN_EPI = false, bool SP2 = false>
; __device__ __forceinline__ void gemm_phase(PG8_LAS unsigned char* lds, const Gemm g, const Sched& S, const Epi& E, const int tid) {
;     ...
;             PG8_WAIT_V(8); PG8_WAIT_L(0); PG8_BAR; PG8_MMA(1, 0, At, B0); PG8_MMA(1, 1, At, B1); PG8_BAR; PG8_SCHED;
;             PG8_LDB(B0, 1, 0); PG8_LDB(B1, 1, 1); PG8_SCHED; PG8_LDA(At, 1, 0); PG8_STAGE(PG8_SA(0, 1), a2 + hstep, voffA);
;             PG8_WAIT_V(8); PG8_WAIT_L(0); PG8_BAR; PG8_MMA(0, 0, At, B0); PG8_MMA(0, 1, At, B1); PG8_BAR; PG8_SCHED;
	v_mfma_f32_16x16x32_bf16 v[80:83], v[44:47], v[194:197], v[80:83]
	v_mfma_f32_16x16x32_bf16 v[64:67], v[44:47], v[202:205], v[64:67]
	v_mfma_f32_16x16x32_bf16 v[40:43], v[44:47], v[210:213], v[40:43]
	v_mfma_f32_16x16x32_bf16 v[16:19], v[44:47], v[218:221], v[16:19]
	v_mfma_f32_16x16x32_bf16 v[76:79], v[160:163], v[194:197], v[76:79]
	v_mfma_f32_16x16x32_bf16 v[60:63], v[160:163], v[202:205], v[60:63]
	v_mfma_f32_16x16x32_bf16 v[34:37], v[160:163], v[210:213], v[36:39]
	v_mfma_f32_16x16x32_bf16 v[12:15], v[160:163], v[218:221], v[12:15]
	v_mfma_f32_16x16x32_bf16 v[80:83], v[48:51], v[198:201], v[80:83]
	v_mfma_f32_16x16x32_bf16 v[64:67], v[48:51], v[206:209], v[64:67]
	v_mfma_f32_16x16x32_bf16 v[40:43], v[48:51], v[214:217], v[40:43]
	v_mfma_f32_16x16x32_bf16 v[16:19], v[48:51], v[222:225], v[16:19]
	v_mfma_f32_16x16x32_bf16 v[76:79], v[172:175], v[198:201], v[76:79]
	v_mfma_f32_16x16x32_bf16 v[60:63], v[172:175], v[206:209], v[60:63]
	v_mfma_f32_16x16x32_bf16 v[34:37], v[172:175], v[214:217], v[34:37]
	v_mfma_f32_16x16x32_bf16 v[12:15], v[172:175], v[222:225], v[12:15]
	s_setprio 0
	s_setprio 1
	v_mfma_f32_16x16x32_bf16 v[56:59], v[176:179], v[202:205], v[56:59]
	v_mfma_f32_16x16x32_bf16 v[24:27], v[176:179], v[210:213], v[24:27]
	v_mfma_f32_16x16x32_bf16 v[8:11], v[176:179], v[218:221], v[8:11]
	v_mfma_f32_16x16x32_bf16 v[44:47], v[176:179], v[194:197], v[72:75]
	v_mfma_f32_16x16x32_bf16 v[52:55], v[186:189], v[202:205], v[52:55]
	v_mfma_f32_16x16x32_bf16 v[20:23], v[186:189], v[210:213], v[20:23]
	v_mfma_f32_16x16x32_bf16 v[4:7], v[186:189], v[218:221], v[4:7]
	v_mfma_f32_16x16x32_bf16 v[48:51], v[186:189], v[194:197], v[68:71]
	v_mfma_f32_16x16x32_bf16 v[56:59], v[180:183], v[206:209], v[56:59]
	v_mfma_f32_16x16x32_bf16 v[24:27], v[180:183], v[214:217], v[24:27]
	v_mfma_f32_16x16x32_bf16 v[8:11], v[180:183], v[222:225], v[8:11]
	v_mfma_f32_16x16x32_bf16 v[44:47], v[180:183], v[198:201], v[44:47]
	v_mfma_f32_16x16x32_bf16 v[52:55], v[190:193], v[206:209], v[52:55]
	v_mfma_f32_16x16x32_bf16 v[20:23], v[190:193], v[214:217], v[20:23]
	v_mfma_f32_16x16x32_bf16 v[4:7], v[190:193], v[222:225], v[4:7]
	v_mfma_f32_16x16x32_bf16 v[48:51], v[190:193], v[198:201], v[48:51]
	s_setprio 0
	s_barrier
	s_add_i32 s3, 0, 0x18000
	v_add_u32_e32 v38, s3, v167
	s_add_i32 s42, 0, 0x1c000
	ds_read_b128 v[68:71], v38
	ds_read_b128 v[72:75], v38 offset:1024
	ds_read_b128 v[160:163], v38 offset:2048
	ds_read_b128 v[172:175], v38 offset:3072
	v_add_u32_e32 v38, s42, v167
	ds_read_b128 v[176:179], v38
	ds_read_b128 v[180:183], v38 offset:1024
	ds_read_b128 v[186:189], v38 offset:2048
	ds_read_b128 v[190:193], v38 offset:3072
	s_add_u32 s30, s30, 0x80000
	s_addc_u32 s31, s31, 0
	s_mov_b32 m0, s52
	v_lshl_add_u64 v[38:39], s[30:31], 0, v[0:1]
	ds_read_b128 v[194:197], v171 offset:32768
	ds_read_b128 v[198:201], v171 offset:33792
	ds_read_b128 v[202:205], v171 offset:34816
	ds_read_b128 v[206:209], v171 offset:35840
	ds_read_b128 v[210:213], v171 offset:36864
	ds_read_b128 v[214:217], v171 offset:37888
	ds_read_b128 v[218:221], v171 offset:38912
	ds_read_b128 v[222:225], v171 offset:39936
	global_load_lds_dwordx4 v[38:39], off
	v_lshl_add_u64 v[38:39], s[30:31], 0, v[148:149]
	s_mov_b32 m0, s53
	s_nop 0
	global_load_lds_dwordx4 v[38:39], off
	s_waitcnt vmcnt(8)
	s_waitcnt lgkmcnt(0)
	s_setprio 1
	s_barrier
	v_mfma_f32_16x16x32_bf16 v[144:147], v[68:71], v[194:197], v[144:147]
	v_mfma_f32_16x16x32_bf16 v[128:131], v[68:71], v[202:205], v[128:131]
	v_mfma_f32_16x16x32_bf16 v[112:115], v[68:71], v[210:213], v[112:115]
	v_mfma_f32_16x16x32_bf16 v[96:99], v[68:71], v[218:221], v[96:99]
	v_mfma_f32_16x16x32_bf16 v[140:143], v[160:163], v[194:197], v[140:143]
	v_mfma_f32_16x16x32_bf16 v[124:127], v[160:163], v[202:205], v[124:127]
	v_mfma_f32_16x16x32_bf16 v[108:111], v[160:163], v[210:213], v[108:111]
	v_mfma_f32_16x16x32_bf16 v[92:95], v[160:163], v[218:221], v[92:95]
	v_mfma_f32_16x16x32_bf16 v[144:147], v[72:75], v[198:201], v[144:147]
	v_mfma_f32_16x16x32_bf16 v[128:131], v[72:75], v[206:209], v[128:131]
	v_mfma_f32_16x16x32_bf16 v[112:115], v[72:75], v[214:217], v[112:115]
	v_mfma_f32_16x16x32_bf16 v[96:99], v[72:75], v[222:225], v[96:99]
	v_mfma_f32_16x16x32_bf16 v[140:143], v[172:175], v[198:201], v[140:143]
	v_mfma_f32_16x16x32_bf16 v[124:127], v[172:175], v[206:209], v[124:127]
	v_mfma_f32_16x16x32_bf16 v[108:111], v[172:175], v[214:217], v[108:111]
	v_mfma_f32_16x16x32_bf16 v[92:95], v[172:175], v[222:225], v[92:95]
	s_setprio 0
	s_setprio 1
	v_mfma_f32_16x16x32_bf16 v[136:139], v[176:179], v[194:197], v[136:139]
	v_mfma_f32_16x16x32_bf16 v[120:123], v[176:179], v[202:205], v[120:123]
	v_mfma_f32_16x16x32_bf16 v[104:107], v[176:179], v[210:213], v[104:107]
	v_mfma_f32_16x16x32_bf16 v[88:91], v[176:179], v[218:221], v[88:91]
	v_mfma_f32_16x16x32_bf16 v[132:135], v[186:189], v[194:197], v[132:135]
	v_mfma_f32_16x16x32_bf16 v[116:119], v[186:189], v[202:205], v[116:119]
	v_mfma_f32_16x16x32_bf16 v[100:103], v[186:189], v[210:213], v[100:103]
	v_mfma_f32_16x16x32_bf16 v[84:87], v[186:189], v[218:221], v[84:87]
	v_mfma_f32_16x16x32_bf16 v[136:139], v[180:183], v[198:201], v[136:139]
	v_mfma_f32_16x16x32_bf16 v[120:123], v[180:183], v[206:209], v[120:123]
	v_mfma_f32_16x16x32_bf16 v[104:107], v[180:183], v[214:217], v[104:107]
	v_mfma_f32_16x16x32_bf16 v[88:91], v[180:183], v[222:225], v[88:91]
	v_mfma_f32_16x16x32_bf16 v[132:135], v[190:193], v[198:201], v[132:135]
	v_mfma_f32_16x16x32_bf16 v[116:119], v[190:193], v[206:209], v[116:119]
	v_mfma_f32_16x16x32_bf16 v[100:103], v[190:193], v[214:217], v[100:103]
	v_mfma_f32_16x16x32_bf16 v[84:87], v[190:193], v[222:225], v[84:87]
	s_setprio 0
	s_barrier
; #define PG8_STAGE(bufoff, gbase, voff) do { _Pragma("unroll") for (int _i = 0; _i < 2; ++_i) \
;         __builtin_amdgcn_global_load_lds((const unsigned*)((const char*)(gbase) + (voff)[_i]), (PG8_LAS unsigned*)(lds + (bufoff) + ldsw + _i * 8192), 16, 0, 0); } while (0)
; #define PG8_LDA(dst, b, h) do { _Pragma("unroll") for (int m = 0; m < 4; ++m) _Pragma("unroll") for (int k = 0; k < 2; ++k) dst[m][k] = *(const PG8_LAS bf16x8*)(lds + PG8_SA(b, h) + aoff + m * 2048 + k * 1024); } while (0)
; #define PG8_MMA(ai, bj, At, Bt) do { __builtin_amdgcn_s_setprio(1); _Pragma("unroll") for (int m = 0; m < 4; ++m) _Pragma("unroll") for (int n = 0; n < 2; ++n) _Pragma("unroll") for (int k = 0; k < 2; ++k) \
;         acc[ai][bj][m][n] = __builtin_amdgcn_mfma_f32_16x16x32_bf16(Bt[n][k], At[m][k], acc[ai][bj][m][n], 0, 0, 0); __builtin_amdgcn_s_setprio(0); } while (0)
; #define PG8_WAIT_V(n) asm volatile("s_waitcnt vmcnt(" #n ")" ::: "memory")
; #define PG8_WAIT_L(n) asm volatile("s_waitcnt lgkmcnt(" #n ")" ::: "memory")
; #define PG8_BAR __builtin_amdgcn_s_barrier()
; #define PG8_SCHED __builtin_amdgcn_sched_barrier(0)
; template <class Epi, class Sched, bool ALIGN_EPI = false, bool SP2 = false>
; __device__ __forceinline__ void gemm_phase(PG8_LAS unsigned char* lds, const Gemm g, const Sched& S, const Epi& E, const int tid) {
;     ...
;             PG8_LDA(At, 1, 1); PG8_STAGE(PG8_SB(1, 0), b3, voffB); PG8_STAGE(PG8_SB(1, 1), b3 + hstep, voffB); PG8_STAGE(PG8_SA(1, 0), a3, voffA);
;             PG8_WAIT_V(8); PG8_WAIT_L(0); PG8_BAR; PG8_MMA(1, 0, At, B0); PG8_MMA(1, 1, At, B1); PG8_BAR; PG8_SCHED;
	s_add_i32 s3, s3, s44
	v_lshl_add_u64 v[38:39], v[164:165], 0, s[46:47]
	s_mov_b32 m0, s3
	ds_read_b128 v[194:197], v171 offset:49152
	ds_read_b128 v[198:201], v171 offset:50176
	ds_read_b128 v[202:205], v171 offset:51200
	ds_read_b128 v[206:209], v171 offset:52224
	ds_read_b128 v[210:213], v171 offset:53248
	ds_read_b128 v[214:217], v171 offset:54272
	ds_read_b128 v[218:221], v171 offset:55296
	ds_read_b128 v[222:225], v171 offset:56320
	global_load_lds_dwordx4 v[38:39], off
	s_add_i32 m0, s3, 0x2000
	s_add_u32 s28, s28, 0x80080
	v_lshl_add_u64 v[38:39], v[226:227], 0, s[46:47]
	s_addc_u32 s29, s29, 0
	s_add_i32 s3, s42, s44
	global_load_lds_dwordx4 v[38:39], off
	v_lshl_add_u64 v[38:39], s[28:29], 0, v[2:3]
	s_mov_b32 m0, s3
	s_nop 0
	global_load_lds_dwordx4 v[38:39], off
	v_lshl_add_u64 v[38:39], s[28:29], 0, v[150:151]
	s_add_i32 m0, s3, 0x2000
	s_nop 0
	global_load_lds_dwordx4 v[38:39], off
	v_lshl_add_u64 v[38:39], v[228:229], 0, s[46:47]
	s_mov_b32 m0, s5
	s_nop 0
	global_load_lds_dwordx4 v[38:39], off
	v_lshl_add_u64 v[38:39], v[230:231], 0, s[46:47]
	s_mov_b32 m0, s54
	s_nop 0
	global_load_lds_dwordx4 v[38:39], off
	s_waitcnt vmcnt(8)
	s_waitcnt lgkmcnt(0)
	s_setprio 1
	s_barrier
	v_mfma_f32_16x16x32_bf16 v[80:83], v[68:71], v[194:197], v[80:83]
	v_mfma_f32_16x16x32_bf16 v[64:67], v[68:71], v[202:205], v[64:67]
	v_mfma_f32_16x16x32_bf16 v[38:41], v[68:71], v[210:213], v[40:43]
	v_mfma_f32_16x16x32_bf16 v[16:19], v[68:71], v[218:221], v[16:19]
	v_mfma_f32_16x16x32_bf16 v[76:79], v[160:163], v[194:197], v[76:79]
	v_mfma_f32_16x16x32_bf16 v[60:63], v[160:163], v[202:205], v[60:63]
	v_mfma_f32_16x16x32_bf16 v[34:37], v[160:163], v[210:213], v[34:37]
	v_mfma_f32_16x16x32_bf16 v[12:15], v[160:163], v[218:221], v[12:15]
	v_mfma_f32_16x16x32_bf16 v[80:83], v[72:75], v[198:201], v[80:83]
	v_mfma_f32_16x16x32_bf16 v[64:67], v[72:75], v[206:209], v[64:67]
	v_mfma_f32_16x16x32_bf16 v[40:43], v[72:75], v[214:217], v[38:41]
	v_mfma_f32_16x16x32_bf16 v[16:19], v[72:75], v[222:225], v[16:19]
	v_mfma_f32_16x16x32_bf16 v[76:79], v[172:175], v[198:201], v[76:79]
	v_mfma_f32_16x16x32_bf16 v[60:63], v[172:175], v[206:209], v[60:63]
	v_mfma_f32_16x16x32_bf16 v[36:39], v[172:175], v[214:217], v[34:37]
	v_mfma_f32_16x16x32_bf16 v[12:15], v[172:175], v[222:225], v[12:15]
	s_setprio 0
	s_setprio 1
	v_mfma_f32_16x16x32_bf16 v[44:47], v[176:179], v[194:197], v[44:47]
	v_mfma_f32_16x16x32_bf16 v[72:75], v[180:183], v[198:201], v[44:47]
	v_mfma_f32_16x16x32_bf16 v[44:47], v[186:189], v[194:197], v[48:51]
	v_mfma_f32_16x16x32_bf16 v[68:71], v[190:193], v[198:201], v[44:47]
	v_mfma_f32_16x16x32_bf16 v[44:47], v[176:179], v[202:205], v[56:59]
	v_mfma_f32_16x16x32_bf16 v[56:59], v[180:183], v[206:209], v[44:47]
	v_mfma_f32_16x16x32_bf16 v[44:47], v[186:189], v[202:205], v[52:55]
	v_mfma_f32_16x16x32_bf16 v[24:27], v[176:179], v[210:213], v[24:27]
	v_mfma_f32_16x16x32_bf16 v[20:23], v[186:189], v[210:213], v[20:23]
	v_mfma_f32_16x16x32_bf16 v[8:11], v[176:179], v[218:221], v[8:11]
	v_mfma_f32_16x16x32_bf16 v[4:7], v[186:189], v[218:221], v[4:7]
	v_mfma_f32_16x16x32_bf16 v[52:55], v[190:193], v[206:209], v[44:47]
	v_mfma_f32_16x16x32_bf16 v[24:27], v[180:183], v[214:217], v[24:27]
	v_mfma_f32_16x16x32_bf16 v[20:23], v[190:193], v[214:217], v[20:23]
	v_mfma_f32_16x16x32_bf16 v[8:11], v[180:183], v[222:225], v[8:11]
	v_mfma_f32_16x16x32_bf16 v[4:7], v[190:193], v[222:225], v[4:7]
	s_setprio 0
	s_barrier
	s_add_i32 s50, s50, 2
	s_add_u32 s26, s26, 0x100
	s_addc_u32 s27, s27, 0
	s_add_u32 s23, s23, 0x100
	s_addc_u32 s25, s25, 0
	s_cmp_gt_u32 s50, 29
	s_cbranch_scc1 .LBB0_159

; #define PG8_STAGE(bufoff, gbase, voff) do { _Pragma("unroll") for (int _i = 0; _i < 2; ++_i) \
;         __builtin_amdgcn_global_load_lds((const unsigned*)((const char*)(gbase) + (voff)[_i]), (PG8_LAS unsigned*)(lds + (bufoff) + ldsw + _i * 8192), 16, 0, 0); } while (0)
; #define PG8_LDA(dst, b, h) do { _Pragma("unroll") for (int m = 0; m < 4; ++m) _Pragma("unroll") for (int k = 0; k < 2; ++k) dst[m][k] = *(const PG8_LAS bf16x8*)(lds + PG8_SA(b, h) + aoff + m * 2048 + k * 1024); } while (0)
; #define PG8_LDB(dst, b, h) do { _Pragma("unroll") for (int n = 0; n < 2; ++n) _Pragma("unroll") for (int k = 0; k < 2; ++k) dst[n][k] = *(const PG8_LAS bf16x8*)(lds + PG8_SB(b, h) + boff + n * 2048 + k * 1024); } while (0)
; #define PG8_MMA(ai, bj, At, Bt) do { __builtin_amdgcn_s_setprio(1); _Pragma("unroll") for (int m = 0; m < 4; ++m) _Pragma("unroll") for (int n = 0; n < 2; ++n) _Pragma("unroll") for (int k = 0; k < 2; ++k) \
;         acc[ai][bj][m][n] = __builtin_amdgcn_mfma_f32_16x16x32_bf16(Bt[n][k], At[m][k], acc[ai][bj][m][n], 0, 0, 0); __builtin_amdgcn_s_setprio(0); } while (0)
; #define PG8_WAIT_V(n) asm volatile("s_waitcnt vmcnt(" #n ")" ::: "memory")
; #define PG8_WAIT_L(n) asm volatile("s_waitcnt lgkmcnt(" #n ")" ::: "memory")
; #define PG8_BAR __builtin_amdgcn_s_barrier()
; #define PG8_SCHED __builtin_amdgcn_sched_barrier(0)
; template <class Epi, class Sched, bool ALIGN_EPI = false, bool SP2 = false>
; __device__ __forceinline__ void gemm_phase(PG8_LAS unsigned char* lds, const Gemm g, const Sched& S, const Epi& E, const int tid) {
;     ...
;             const char* a1 = cA + (size_t)(t + 1) * kstep;
;             const char* a2 = last ? nA : cA + (size_t)(t + 2) * kstep; const char* b2 = last ? nB : cB + (size_t)(t + 2) * kstep;
;             const char* a3 = a2 + kstep; const char* b3 = b2 + kstep;
;             if (last && has_next) S.a_ready(nxt);
;             if (last) E.prefetch(lds + EPI_LDS_OFF + wid * 1024, cur, wr, wc, lane);
;             if constexpr (SP2) {
;             PG8_LDB(B0, 0, 0); PG8_LDB(B1, 0, 1); PG8_SCHED; PG8_LDA(At, 0, 0); PG8_STAGE(PG8_SA(1, 1), a1 + hstep, voffA);
;             PG8_WAIT_V(8); PG8_WAIT_L(0); PG8_BAR; PG8_MMA(0, 0, At, B0); PG8_MMA(0, 1, At, B1); PG8_BAR; PG8_SCHED;
;             PG8_LDA(At, 0, 1); PG8_STAGE(PG8_SB(0, 0), b2, voffB); PG8_STAGE(PG8_SB(0, 1), b2 + hstep, voffB); PG8_STAGE(PG8_SA(0, 0), a2, voffA);
.LBB0_228:
	s_add_u32 s22, s20, 0x100
	s_addc_u32 s23, s21, 0
	s_and_b64 s[24:25], s[24:25], exec
	s_cselect_b32 s27, s11, s23
	s_cselect_b32 s26, s10, s22
	s_cselect_b32 s25, s17, s75
	s_cselect_b32 s24, s16, s74
	s_add_i32 s42, 0, 0x10000
	s_add_i32 s43, 0, 0x14000
	v_add_u32_e32 v146, s42, v220
	v_add_u32_e32 v162, s43, v220
	ds_read_b128 v[134:137], v146
	ds_read_b128 v[138:141], v146 offset:1024
	ds_read_b128 v[142:145], v146 offset:2048
	ds_read_b128 v[146:149], v146 offset:3072
	ds_read_b128 v[150:153], v162
	ds_read_b128 v[154:157], v162 offset:1024
	ds_read_b128 v[158:161], v162 offset:2048
	ds_read_b128 v[172:175], v162 offset:3072
	v_lshl_add_u64 v[162:163], s[20:21], 0, v[168:169]
	s_add_i32 m0, s30, 0xc000
	ds_read_b128 v[176:179], v226
	ds_read_b128 v[186:189], v226 offset:1024
	ds_read_b128 v[190:193], v226 offset:2048
	ds_read_b128 v[194:197], v226 offset:3072
	ds_read_b128 v[198:201], v226 offset:4096
	ds_read_b128 v[202:205], v226 offset:5120
	ds_read_b128 v[206:209], v226 offset:6144
	ds_read_b128 v[210:213], v226 offset:7168
	global_load_lds_dwordx4 v[162:163], off
	v_lshl_add_u64 v[162:163], s[20:21], 0, v[170:171]
	s_add_i32 m0, s30, 0xe000
	s_nop 0
	global_load_lds_dwordx4 v[162:163], off
	s_waitcnt vmcnt(8)
	s_waitcnt lgkmcnt(0)
	s_setprio 1
	s_barrier
	v_mfma_f32_16x16x32_bf16 v[128:131], v[134:137], v[176:179], v[128:131]
	v_mfma_f32_16x16x32_bf16 v[112:115], v[134:137], v[190:193], v[112:115]
	v_mfma_f32_16x16x32_bf16 v[96:99], v[134:137], v[198:201], v[96:99]
	v_mfma_f32_16x16x32_bf16 v[80:83], v[134:137], v[206:209], v[80:83]
	v_mfma_f32_16x16x32_bf16 v[124:127], v[142:145], v[176:179], v[124:127]
	v_mfma_f32_16x16x32_bf16 v[108:111], v[142:145], v[190:193], v[108:111]
	v_mfma_f32_16x16x32_bf16 v[92:95], v[142:145], v[198:201], v[92:95]
	v_mfma_f32_16x16x32_bf16 v[76:79], v[142:145], v[206:209], v[76:79]
	v_mfma_f32_16x16x32_bf16 v[128:131], v[138:141], v[186:189], v[128:131]
	v_mfma_f32_16x16x32_bf16 v[112:115], v[138:141], v[194:197], v[112:115]
	v_mfma_f32_16x16x32_bf16 v[96:99], v[138:141], v[202:205], v[96:99]
	v_mfma_f32_16x16x32_bf16 v[80:83], v[138:141], v[210:213], v[80:83]
	v_mfma_f32_16x16x32_bf16 v[124:127], v[146:149], v[186:189], v[124:127]
	v_mfma_f32_16x16x32_bf16 v[108:111], v[146:149], v[194:197], v[108:111]
	v_mfma_f32_16x16x32_bf16 v[92:95], v[146:149], v[202:205], v[92:95]
	v_mfma_f32_16x16x32_bf16 v[76:79], v[146:149], v[210:213], v[76:79]
	s_setprio 0
	s_setprio 1
	v_mfma_f32_16x16x32_bf16 v[120:123], v[150:153], v[176:179], v[120:123]
	v_mfma_f32_16x16x32_bf16 v[104:107], v[150:153], v[190:193], v[104:107]
	v_mfma_f32_16x16x32_bf16 v[88:91], v[150:153], v[198:201], v[88:91]
	v_mfma_f32_16x16x32_bf16 v[72:75], v[150:153], v[206:209], v[72:75]
	v_mfma_f32_16x16x32_bf16 v[116:119], v[158:161], v[176:179], v[116:119]
	v_mfma_f32_16x16x32_bf16 v[100:103], v[158:161], v[190:193], v[100:103]
	v_mfma_f32_16x16x32_bf16 v[84:87], v[158:161], v[198:201], v[84:87]
	v_mfma_f32_16x16x32_bf16 v[68:71], v[158:161], v[206:209], v[68:71]
	v_mfma_f32_16x16x32_bf16 v[120:123], v[154:157], v[186:189], v[120:123]
	v_mfma_f32_16x16x32_bf16 v[104:107], v[154:157], v[194:197], v[104:107]
	v_mfma_f32_16x16x32_bf16 v[88:91], v[154:157], v[202:205], v[88:91]
	v_mfma_f32_16x16x32_bf16 v[72:75], v[154:157], v[210:213], v[72:75]
	v_mfma_f32_16x16x32_bf16 v[116:119], v[172:175], v[186:189], v[116:119]
	v_mfma_f32_16x16x32_bf16 v[100:103], v[172:175], v[194:197], v[100:103]
	v_mfma_f32_16x16x32_bf16 v[84:87], v[172:175], v[202:205], v[84:87]
	v_mfma_f32_16x16x32_bf16 v[68:71], v[172:175], v[210:213], v[68:71]
	s_setprio 0
	s_barrier
	s_add_i32 s20, s42, s29
	v_lshl_add_u64 v[162:163], s[24:25], 0, v[2:3]
	s_mov_b32 m0, s20
	ds_read_b128 v[176:179], v226 offset:16384
	ds_read_b128 v[186:189], v226 offset:17408
	ds_read_b128 v[190:193], v226 offset:18432
	ds_read_b128 v[194:197], v226 offset:19456
	ds_read_b128 v[198:201], v226 offset:20480
	ds_read_b128 v[202:205], v226 offset:21504
	ds_read_b128 v[206:209], v226 offset:22528
	ds_read_b128 v[210:213], v226 offset:23552
	global_load_lds_dwordx4 v[162:163], off
	s_add_i32 m0, s20, 0x2000
	s_add_u32 s20, s24, 0x160000
	v_lshl_add_u64 v[180:181], s[24:25], 0, v[166:167]
	s_addc_u32 s21, s25, 0
	s_add_i32 s42, s43, s29
	global_load_lds_dwordx4 v[180:181], off
	v_lshl_add_u64 v[182:183], s[20:21], 0, v[2:3]
	s_mov_b32 m0, s42
	v_lshl_add_u64 v[214:215], s[26:27], 0, v[164:165]
	global_load_lds_dwordx4 v[182:183], off
	v_lshl_add_u64 v[182:183], s[20:21], 0, v[166:167]
	s_add_i32 m0, s42, 0x2000
	s_nop 0
	global_load_lds_dwordx4 v[182:183], off
	v_lshl_add_u64 v[182:183], s[26:27], 0, v[0:1]
	s_mov_b32 m0, s30
	s_nop 0
	global_load_lds_dwordx4 v[182:183], off
	s_mov_b32 m0, s31
	s_nop 0
	global_load_lds_dwordx4 v[214:215], off
	s_waitcnt vmcnt(8)
	s_waitcnt lgkmcnt(0)
	s_setprio 1
	s_barrier
; #define PG8_STAGE(bufoff, gbase, voff) do { _Pragma("unroll") for (int _i = 0; _i < 2; ++_i) \
;         __builtin_amdgcn_global_load_lds((const unsigned*)((const char*)(gbase) + (voff)[_i]), (PG8_LAS unsigned*)(lds + (bufoff) + ldsw + _i * 8192), 16, 0, 0); } while (0)
; #define PG8_LDA(dst, b, h) do { _Pragma("unroll") for (int m = 0; m < 4; ++m) _Pragma("unroll") for (int k = 0; k < 2; ++k) dst[m][k] = *(const PG8_LAS bf16x8*)(lds + PG8_SA(b, h) + aoff + m * 2048 + k * 1024); } while (0)
; #define PG8_LDB(dst, b, h) do { _Pragma("unroll") for (int n = 0; n < 2; ++n) _Pragma("unroll") for (int k = 0; k < 2; ++k) dst[n][k] = *(const PG8_LAS bf16x8*)(lds + PG8_SB(b, h) + boff + n * 2048 + k * 1024); } while (0)
; #define PG8_MMA(ai, bj, At, Bt) do { __builtin_amdgcn_s_setprio(1); _Pragma("unroll") for (int m = 0; m < 4; ++m) _Pragma("unroll") for (int n = 0; n < 2; ++n) _Pragma("unroll") for (int k = 0; k < 2; ++k) \
;         acc[ai][bj][m][n] = __builtin_amdgcn_mfma_f32_16x16x32_bf16(Bt[n][k], At[m][k], acc[ai][bj][m][n], 0, 0, 0); __builtin_amdgcn_s_setprio(0); } while (0)
; #define PG8_WAIT_V(n) asm volatile("s_waitcnt vmcnt(" #n ")" ::: "memory")
; #define PG8_WAIT_L(n) asm volatile("s_waitcnt lgkmcnt(" #n ")" ::: "memory")
; #define PG8_BAR __builtin_amdgcn_s_barrier()
; #define PG8_SCHED __builtin_amdgcn_sched_barrier(0)
; template <class Epi, class Sched, bool ALIGN_EPI = false, bool SP2 = false>
; __device__ __forceinline__ void gemm_phase(PG8_LAS unsigned char* lds, const Gemm g, const Sched& S, const Epi& E, const int tid) {
;     ...
;             PG8_WAIT_V(8); PG8_WAIT_L(0); PG8_BAR; PG8_MMA(1, 0, At, B0); PG8_MMA(1, 1, At, B1); PG8_BAR; PG8_SCHED;
;             PG8_LDB(B0, 1, 0); PG8_LDB(B1, 1, 1); PG8_SCHED; PG8_LDA(At, 1, 0); PG8_STAGE(PG8_SA(0, 1), a2 + hstep, voffA);
;             PG8_WAIT_V(8); PG8_WAIT_L(0); PG8_BAR; PG8_MMA(0, 0, At, B0); PG8_MMA(0, 1, At, B1); PG8_BAR; PG8_SCHED;
	v_mfma_f32_16x16x32_bf16 v[64:67], v[134:137], v[176:179], v[64:67]
	v_mfma_f32_16x16x32_bf16 v[48:51], v[134:137], v[190:193], v[48:51]
	v_mfma_f32_16x16x32_bf16 v[32:35], v[134:137], v[198:201], v[32:35]
	v_mfma_f32_16x16x32_bf16 v[16:19], v[134:137], v[206:209], v[16:19]
	v_mfma_f32_16x16x32_bf16 v[60:63], v[142:145], v[176:179], v[60:63]
	v_mfma_f32_16x16x32_bf16 v[44:47], v[142:145], v[190:193], v[44:47]
	v_mfma_f32_16x16x32_bf16 v[28:31], v[142:145], v[198:201], v[28:31]
	v_mfma_f32_16x16x32_bf16 v[12:15], v[142:145], v[206:209], v[12:15]
	v_mfma_f32_16x16x32_bf16 v[64:67], v[138:141], v[186:189], v[64:67]
	v_mfma_f32_16x16x32_bf16 v[48:51], v[138:141], v[194:197], v[48:51]
	v_mfma_f32_16x16x32_bf16 v[32:35], v[138:141], v[202:205], v[32:35]
	v_mfma_f32_16x16x32_bf16 v[16:19], v[138:141], v[210:213], v[16:19]
	v_mfma_f32_16x16x32_bf16 v[60:63], v[146:149], v[186:189], v[60:63]
	v_mfma_f32_16x16x32_bf16 v[44:47], v[146:149], v[194:197], v[44:47]
	v_mfma_f32_16x16x32_bf16 v[28:31], v[146:149], v[202:205], v[28:31]
	v_mfma_f32_16x16x32_bf16 v[12:15], v[146:149], v[210:213], v[12:15]
	s_setprio 0
	s_setprio 1
	v_mfma_f32_16x16x32_bf16 v[56:59], v[150:153], v[176:179], v[56:59]
	v_mfma_f32_16x16x32_bf16 v[40:43], v[150:153], v[190:193], v[40:43]
	v_mfma_f32_16x16x32_bf16 v[24:27], v[150:153], v[198:201], v[24:27]
	v_mfma_f32_16x16x32_bf16 v[8:11], v[150:153], v[206:209], v[8:11]
	v_mfma_f32_16x16x32_bf16 v[52:55], v[158:161], v[176:179], v[52:55]
	v_mfma_f32_16x16x32_bf16 v[36:39], v[158:161], v[190:193], v[36:39]
	v_mfma_f32_16x16x32_bf16 v[20:23], v[158:161], v[198:201], v[20:23]
	v_mfma_f32_16x16x32_bf16 v[4:7], v[158:161], v[206:209], v[4:7]
	v_mfma_f32_16x16x32_bf16 v[56:59], v[154:157], v[186:189], v[56:59]
	v_mfma_f32_16x16x32_bf16 v[40:43], v[154:157], v[194:197], v[40:43]
	v_mfma_f32_16x16x32_bf16 v[24:27], v[154:157], v[202:205], v[24:27]
	v_mfma_f32_16x16x32_bf16 v[8:11], v[154:157], v[210:213], v[8:11]
	v_mfma_f32_16x16x32_bf16 v[52:55], v[172:175], v[186:189], v[52:55]
	v_mfma_f32_16x16x32_bf16 v[36:39], v[172:175], v[194:197], v[36:39]
	v_mfma_f32_16x16x32_bf16 v[20:23], v[172:175], v[202:205], v[20:23]
	v_mfma_f32_16x16x32_bf16 v[4:7], v[172:175], v[210:213], v[4:7]
	s_setprio 0
	s_barrier
	s_add_i32 s42, 0, 0x18000
	s_add_i32 s43, 0, 0x1c000
	v_add_u32_e32 v146, s42, v220
	v_add_u32_e32 v172, s43, v220
	ds_read_b128 v[134:137], v146
	ds_read_b128 v[138:141], v146 offset:1024
	ds_read_b128 v[142:145], v146 offset:2048
	ds_read_b128 v[146:149], v146 offset:3072
	ds_read_b128 v[150:153], v172
	ds_read_b128 v[154:157], v172 offset:1024
	ds_read_b128 v[158:161], v172 offset:2048
	ds_read_b128 v[172:175], v172 offset:3072
	s_add_u32 s20, s26, 0x160000
	s_addc_u32 s21, s27, 0
	s_mov_b32 m0, s36
	v_lshl_add_u64 v[216:217], s[20:21], 0, v[0:1]
	ds_read_b128 v[176:179], v226 offset:32768
	ds_read_b128 v[186:189], v226 offset:33792
	ds_read_b128 v[190:193], v226 offset:34816
	ds_read_b128 v[194:197], v226 offset:35840
	ds_read_b128 v[198:201], v226 offset:36864
	ds_read_b128 v[202:205], v226 offset:37888
	ds_read_b128 v[206:209], v226 offset:38912
	ds_read_b128 v[210:213], v226 offset:39936
	global_load_lds_dwordx4 v[216:217], off
	v_lshl_add_u64 v[216:217], s[20:21], 0, v[164:165]
	s_mov_b32 m0, s37
	s_nop 0
	global_load_lds_dwordx4 v[216:217], off
	s_waitcnt vmcnt(8)
	s_waitcnt lgkmcnt(0)
	s_setprio 1
	s_barrier
	v_mfma_f32_16x16x32_bf16 v[128:131], v[134:137], v[176:179], v[128:131]
	v_mfma_f32_16x16x32_bf16 v[112:115], v[134:137], v[190:193], v[112:115]
	v_mfma_f32_16x16x32_bf16 v[96:99], v[134:137], v[198:201], v[96:99]
	v_mfma_f32_16x16x32_bf16 v[80:83], v[134:137], v[206:209], v[80:83]
	v_mfma_f32_16x16x32_bf16 v[124:127], v[142:145], v[176:179], v[124:127]
	v_mfma_f32_16x16x32_bf16 v[108:111], v[142:145], v[190:193], v[108:111]
	v_mfma_f32_16x16x32_bf16 v[92:95], v[142:145], v[198:201], v[92:95]
	v_mfma_f32_16x16x32_bf16 v[76:79], v[142:145], v[206:209], v[76:79]
	v_mfma_f32_16x16x32_bf16 v[128:131], v[138:141], v[186:189], v[128:131]
	v_mfma_f32_16x16x32_bf16 v[112:115], v[138:141], v[194:197], v[112:115]
	v_mfma_f32_16x16x32_bf16 v[96:99], v[138:141], v[202:205], v[96:99]
	v_mfma_f32_16x16x32_bf16 v[80:83], v[138:141], v[210:213], v[80:83]
	v_mfma_f32_16x16x32_bf16 v[124:127], v[146:149], v[186:189], v[124:127]
	v_mfma_f32_16x16x32_bf16 v[108:111], v[146:149], v[194:197], v[108:111]
	v_mfma_f32_16x16x32_bf16 v[92:95], v[146:149], v[202:205], v[92:95]
	v_mfma_f32_16x16x32_bf16 v[76:79], v[146:149], v[210:213], v[76:79]
	s_setprio 0
	s_setprio 1
	v_mfma_f32_16x16x32_bf16 v[120:123], v[150:153], v[176:179], v[120:123]
	v_mfma_f32_16x16x32_bf16 v[104:107], v[150:153], v[190:193], v[104:107]
	v_mfma_f32_16x16x32_bf16 v[88:91], v[150:153], v[198:201], v[88:91]
	v_mfma_f32_16x16x32_bf16 v[72:75], v[150:153], v[206:209], v[72:75]
	v_mfma_f32_16x16x32_bf16 v[116:119], v[158:161], v[176:179], v[116:119]
	v_mfma_f32_16x16x32_bf16 v[100:103], v[158:161], v[190:193], v[100:103]
	v_mfma_f32_16x16x32_bf16 v[84:87], v[158:161], v[198:201], v[84:87]
	v_mfma_f32_16x16x32_bf16 v[68:71], v[158:161], v[206:209], v[68:71]
	v_mfma_f32_16x16x32_bf16 v[120:123], v[154:157], v[186:189], v[120:123]
	v_mfma_f32_16x16x32_bf16 v[104:107], v[154:157], v[194:197], v[104:107]
	v_mfma_f32_16x16x32_bf16 v[88:91], v[154:157], v[202:205], v[88:91]
	v_mfma_f32_16x16x32_bf16 v[72:75], v[154:157], v[210:213], v[72:75]
	v_mfma_f32_16x16x32_bf16 v[116:119], v[172:175], v[186:189], v[116:119]
	v_mfma_f32_16x16x32_bf16 v[100:103], v[172:175], v[194:197], v[100:103]
	v_mfma_f32_16x16x32_bf16 v[84:87], v[172:175], v[202:205], v[84:87]
	v_mfma_f32_16x16x32_bf16 v[68:71], v[172:175], v[210:213], v[68:71]
	s_setprio 0
	s_barrier
; #define PG8_STAGE(bufoff, gbase, voff) do { _Pragma("unroll") for (int _i = 0; _i < 2; ++_i) \
;         __builtin_amdgcn_global_load_lds((const unsigned*)((const char*)(gbase) + (voff)[_i]), (PG8_LAS unsigned*)(lds + (bufoff) + ldsw + _i * 8192), 16, 0, 0); } while (0)
; #define PG8_LDA(dst, b, h) do { _Pragma("unroll") for (int m = 0; m < 4; ++m) _Pragma("unroll") for (int k = 0; k < 2; ++k) dst[m][k] = *(const PG8_LAS bf16x8*)(lds + PG8_SA(b, h) + aoff + m * 2048 + k * 1024); } while (0)
; #define PG8_MMA(ai, bj, At, Bt) do { __builtin_amdgcn_s_setprio(1); _Pragma("unroll") for (int m = 0; m < 4; ++m) _Pragma("unroll") for (int n = 0; n < 2; ++n) _Pragma("unroll") for (int k = 0; k < 2; ++k) \
;         acc[ai][bj][m][n] = __builtin_amdgcn_mfma_f32_16x16x32_bf16(Bt[n][k], At[m][k], acc[ai][bj][m][n], 0, 0, 0); __builtin_amdgcn_s_setprio(0); } while (0)
; #define PG8_WAIT_V(n) asm volatile("s_waitcnt vmcnt(" #n ")" ::: "memory")
; #define PG8_WAIT_L(n) asm volatile("s_waitcnt lgkmcnt(" #n ")" ::: "memory")
; #define PG8_BAR __builtin_amdgcn_s_barrier()
; #define PG8_SCHED __builtin_amdgcn_sched_barrier(0)
; template <class Epi, class Sched, bool ALIGN_EPI = false, bool SP2 = false>
; __device__ __forceinline__ void gemm_phase(PG8_LAS unsigned char* lds, const Gemm g, const Sched& S, const Epi& E, const int tid) {
;     ...
;             PG8_LDA(At, 1, 1); PG8_STAGE(PG8_SB(1, 0), b3, voffB); PG8_STAGE(PG8_SB(1, 1), b3 + hstep, voffB); PG8_STAGE(PG8_SA(1, 0), a3, voffA);
;             PG8_WAIT_V(8); PG8_WAIT_L(0); PG8_BAR; PG8_MMA(1, 0, At, B0); PG8_MMA(1, 1, At, B1); PG8_BAR; PG8_SCHED;
	s_add_i32 s20, s42, s29
	v_lshl_add_u64 v[162:163], v[162:163], 0, s[46:47]
	s_mov_b32 m0, s20
	ds_read_b128 v[176:179], v226 offset:49152
	ds_read_b128 v[186:189], v226 offset:50176
	ds_read_b128 v[190:193], v226 offset:51200
	ds_read_b128 v[194:197], v226 offset:52224
	ds_read_b128 v[198:201], v226 offset:53248
	ds_read_b128 v[202:205], v226 offset:54272
	ds_read_b128 v[206:209], v226 offset:55296
	ds_read_b128 v[210:213], v226 offset:56320
	global_load_lds_dwordx4 v[162:163], off
	s_add_i32 m0, s20, 0x2000
	s_add_u32 s20, s24, 0x160080
	v_lshl_add_u64 v[162:163], v[180:181], 0, s[46:47]
	s_addc_u32 s21, s25, 0
	s_add_i32 s24, s43, s29
	global_load_lds_dwordx4 v[162:163], off
	v_lshl_add_u64 v[162:163], s[20:21], 0, v[2:3]
	s_mov_b32 m0, s24
	s_nop 0
	global_load_lds_dwordx4 v[162:163], off
	v_lshl_add_u64 v[162:163], s[20:21], 0, v[166:167]
	s_add_i32 m0, s24, 0x2000
	s_nop 0
	global_load_lds_dwordx4 v[162:163], off
	v_lshl_add_u64 v[162:163], v[182:183], 0, s[46:47]
	s_mov_b32 m0, s39
	s_nop 0
	global_load_lds_dwordx4 v[162:163], off
	v_lshl_add_u64 v[162:163], v[214:215], 0, s[46:47]
	s_mov_b32 m0, s44
	s_nop 0
	global_load_lds_dwordx4 v[162:163], off
	s_waitcnt vmcnt(8)
	s_waitcnt lgkmcnt(0)
	s_setprio 1
	s_barrier
	v_mfma_f32_16x16x32_bf16 v[64:67], v[134:137], v[176:179], v[64:67]
	v_mfma_f32_16x16x32_bf16 v[48:51], v[134:137], v[190:193], v[48:51]
	v_mfma_f32_16x16x32_bf16 v[32:35], v[134:137], v[198:201], v[32:35]
	v_mfma_f32_16x16x32_bf16 v[16:19], v[134:137], v[206:209], v[16:19]
	v_mfma_f32_16x16x32_bf16 v[60:63], v[142:145], v[176:179], v[60:63]
	v_mfma_f32_16x16x32_bf16 v[44:47], v[142:145], v[190:193], v[44:47]
	v_mfma_f32_16x16x32_bf16 v[28:31], v[142:145], v[198:201], v[28:31]
	v_mfma_f32_16x16x32_bf16 v[12:15], v[142:145], v[206:209], v[12:15]
	v_mfma_f32_16x16x32_bf16 v[64:67], v[138:141], v[186:189], v[64:67]
	v_mfma_f32_16x16x32_bf16 v[48:51], v[138:141], v[194:197], v[48:51]
	v_mfma_f32_16x16x32_bf16 v[32:35], v[138:141], v[202:205], v[32:35]
	v_mfma_f32_16x16x32_bf16 v[16:19], v[138:141], v[210:213], v[16:19]
	v_mfma_f32_16x16x32_bf16 v[60:63], v[146:149], v[186:189], v[60:63]
	v_mfma_f32_16x16x32_bf16 v[44:47], v[146:149], v[194:197], v[44:47]
	v_mfma_f32_16x16x32_bf16 v[28:31], v[146:149], v[202:205], v[28:31]
	v_mfma_f32_16x16x32_bf16 v[12:15], v[146:149], v[210:213], v[12:15]
	s_setprio 0
	s_setprio 1
	v_mfma_f32_16x16x32_bf16 v[56:59], v[150:153], v[176:179], v[56:59]
	v_mfma_f32_16x16x32_bf16 v[40:43], v[150:153], v[190:193], v[40:43]
	v_mfma_f32_16x16x32_bf16 v[24:27], v[150:153], v[198:201], v[24:27]
	v_mfma_f32_16x16x32_bf16 v[8:11], v[150:153], v[206:209], v[8:11]
	v_mfma_f32_16x16x32_bf16 v[52:55], v[158:161], v[176:179], v[52:55]
	v_mfma_f32_16x16x32_bf16 v[36:39], v[158:161], v[190:193], v[36:39]
	v_mfma_f32_16x16x32_bf16 v[20:23], v[158:161], v[198:201], v[20:23]
	v_mfma_f32_16x16x32_bf16 v[4:7], v[158:161], v[206:209], v[4:7]
	v_mfma_f32_16x16x32_bf16 v[56:59], v[154:157], v[186:189], v[56:59]
	v_mfma_f32_16x16x32_bf16 v[40:43], v[154:157], v[194:197], v[40:43]
	v_mfma_f32_16x16x32_bf16 v[24:27], v[154:157], v[202:205], v[24:27]
	v_mfma_f32_16x16x32_bf16 v[8:11], v[154:157], v[210:213], v[8:11]
	v_mfma_f32_16x16x32_bf16 v[52:55], v[172:175], v[186:189], v[52:55]
	v_mfma_f32_16x16x32_bf16 v[36:39], v[172:175], v[194:197], v[36:39]
	v_mfma_f32_16x16x32_bf16 v[20:23], v[172:175], v[202:205], v[20:23]
	v_mfma_f32_16x16x32_bf16 v[4:7], v[172:175], v[210:213], v[4:7]
	s_setprio 0
	s_barrier
	s_add_i32 s84, s84, 2
	s_add_u32 s74, s74, 0x100
	s_addc_u32 s75, s75, 0
	s_cmpk_gt_u32 s84, 0x55
	s_mov_b64 s[20:21], s[22:23]
	s_cbranch_scc1 .LBB0_231

; #define PG8_STAGE(bufoff, gbase, voff) do { _Pragma("unroll") for (int _i = 0; _i < 2; ++_i) \
;         __builtin_amdgcn_global_load_lds((const unsigned*)((const char*)(gbase) + (voff)[_i]), (PG8_LAS unsigned*)(lds + (bufoff) + ldsw + _i * 8192), 16, 0, 0); } while (0)
; #define PG8_LDA(dst, b, h) do { _Pragma("unroll") for (int m = 0; m < 4; ++m) _Pragma("unroll") for (int k = 0; k < 2; ++k) dst[m][k] = *(const PG8_LAS bf16x8*)(lds + PG8_SA(b, h) + aoff + m * 2048 + k * 1024); } while (0)
; #define PG8_LDB(dst, b, h) do { _Pragma("unroll") for (int n = 0; n < 2; ++n) _Pragma("unroll") for (int k = 0; k < 2; ++k) dst[n][k] = *(const PG8_LAS bf16x8*)(lds + PG8_SB(b, h) + boff + n * 2048 + k * 1024); } while (0)
; #define PG8_MMA(ai, bj, At, Bt) do { __builtin_amdgcn_s_setprio(1); _Pragma("unroll") for (int m = 0; m < 4; ++m) _Pragma("unroll") for (int n = 0; n < 2; ++n) _Pragma("unroll") for (int k = 0; k < 2; ++k) \
;         acc[ai][bj][m][n] = __builtin_amdgcn_mfma_f32_16x16x32_bf16(Bt[n][k], At[m][k], acc[ai][bj][m][n], 0, 0, 0); __builtin_amdgcn_s_setprio(0); } while (0)
; #define PG8_WAIT_V(n) asm volatile("s_waitcnt vmcnt(" #n ")" ::: "memory")
; #define PG8_BAR __builtin_amdgcn_s_barrier()
; template <class Epi, class Sched, bool ALIGN_EPI = false, bool SP2 = false>
; __device__ __forceinline__ void gemm_phase(PG8_LAS unsigned char* lds, const Gemm g, const Sched& S, const Epi& E, const int tid) {
;     ...
;             const char* a1 = cA + (size_t)(t + 1) * kstep;
;             const char* a2 = last ? nA : cA + (size_t)(t + 2) * kstep; const char* b2 = last ? nB : cB + (size_t)(t + 2) * kstep;
;             const char* a3 = a2 + kstep; const char* b3 = b2 + kstep;
;             if (last && has_next) S.a_ready(nxt);
;             if (last) E.prefetch(lds + EPI_LDS_OFF + wid * 1024, cur, wr, wc, lane);
;             if constexpr (SP2) {
;             PG8_LDB(B0, 0, 0); PG8_LDB(B1, 0, 1); PG8_SCHED; PG8_LDA(At, 0, 0); PG8_STAGE(PG8_SA(1, 1), a1 + hstep, voffA);
;             PG8_WAIT_V(8); PG8_WAIT_L(0); PG8_BAR; PG8_MMA(0, 0, At, B0); PG8_MMA(0, 1, At, B1); PG8_BAR; PG8_SCHED;
;             PG8_LDA(At, 0, 1); PG8_STAGE(PG8_SB(0, 0), b2, voffB); PG8_STAGE(PG8_SB(0, 1), b2 + hstep, voffB); PG8_STAGE(PG8_SA(0, 0), a2, voffA);
;             PG8_WAIT_V(8); PG8_WAIT_L(0); PG8_BAR; PG8_MMA(1, 0, At, B0); PG8_MMA(1, 1, At, B1); PG8_BAR; PG8_SCHED;
.LBB0_266:
	s_add_u32 s28, s24, 0xfff80080
	s_addc_u32 s29, s25, -1
	s_and_b64 s[26:27], s[26:27], exec
	s_cselect_b32 s29, s17, s29
	s_cselect_b32 s28, s75, s28
	s_cselect_b32 s27, s15, s50
	s_cselect_b32 s26, s85, s23
	s_add_i32 s42, 0, 0x10000
	v_add_u32_e32 v134, s42, v161
	s_add_i32 s43, 0, 0x14000
	ds_read_b128 v[140:143], v134
	ds_read_b128 v[144:147], v134 offset:1024
	ds_read_b128 v[166:169], v134 offset:2048
	ds_read_b128 v[170:173], v134 offset:3072
	v_add_u32_e32 v134, s43, v161
	ds_read_b128 v[174:177], v134
	ds_read_b128 v[186:189], v134 offset:1024
	ds_read_b128 v[190:193], v134 offset:2048
	ds_read_b128 v[194:197], v134 offset:3072
	v_lshl_add_u64 v[134:135], s[24:25], 0, v[156:157]
	s_add_i32 m0, s37, 0xc000
	ds_read_b128 v[198:201], v165
	ds_read_b128 v[202:205], v165 offset:1024
	ds_read_b128 v[206:209], v165 offset:2048
	ds_read_b128 v[210:213], v165 offset:3072
	ds_read_b128 v[214:217], v165 offset:4096
	ds_read_b128 v[218:221], v165 offset:5120
	ds_read_b128 v[222:225], v165 offset:6144
	ds_read_b128 v[226:229], v165 offset:7168
	global_load_lds_dwordx4 v[134:135], off
	v_lshl_add_u64 v[134:135], s[24:25], 0, v[158:159]
	s_add_i32 m0, s37, 0xe000
	s_nop 0
	global_load_lds_dwordx4 v[134:135], off
	s_waitcnt vmcnt(8)
	s_waitcnt lgkmcnt(0)
	s_setprio 1
	s_barrier
	v_mfma_f32_16x16x32_bf16 v[134:137], v[140:143], v[198:201], v[136:139]
	v_mfma_f32_16x16x32_bf16 v[112:115], v[140:143], v[206:209], v[112:115]
	v_mfma_f32_16x16x32_bf16 v[96:99], v[140:143], v[214:217], v[96:99]
	v_mfma_f32_16x16x32_bf16 v[80:83], v[140:143], v[222:225], v[80:83]
	v_mfma_f32_16x16x32_bf16 v[124:127], v[166:169], v[198:201], v[124:127]
	v_mfma_f32_16x16x32_bf16 v[108:111], v[166:169], v[206:209], v[108:111]
	v_mfma_f32_16x16x32_bf16 v[92:95], v[166:169], v[214:217], v[92:95]
	v_mfma_f32_16x16x32_bf16 v[76:79], v[166:169], v[222:225], v[76:79]
	v_mfma_f32_16x16x32_bf16 v[134:137], v[144:147], v[202:205], v[134:137]
	v_mfma_f32_16x16x32_bf16 v[112:115], v[144:147], v[210:213], v[112:115]
	v_mfma_f32_16x16x32_bf16 v[96:99], v[144:147], v[218:221], v[96:99]
	v_mfma_f32_16x16x32_bf16 v[80:83], v[144:147], v[226:229], v[80:83]
	v_mfma_f32_16x16x32_bf16 v[124:127], v[170:173], v[202:205], v[124:127]
	v_mfma_f32_16x16x32_bf16 v[108:111], v[170:173], v[210:213], v[108:111]
	v_mfma_f32_16x16x32_bf16 v[92:95], v[170:173], v[218:221], v[92:95]
	v_mfma_f32_16x16x32_bf16 v[76:79], v[170:173], v[226:229], v[76:79]
	s_setprio 0
	s_setprio 1
	v_mfma_f32_16x16x32_bf16 v[120:123], v[174:177], v[198:201], v[120:123]
	v_mfma_f32_16x16x32_bf16 v[104:107], v[174:177], v[206:209], v[104:107]
	v_mfma_f32_16x16x32_bf16 v[88:91], v[174:177], v[214:217], v[88:91]
	v_mfma_f32_16x16x32_bf16 v[72:75], v[174:177], v[222:225], v[72:75]
	v_mfma_f32_16x16x32_bf16 v[116:119], v[190:193], v[198:201], v[116:119]
	v_mfma_f32_16x16x32_bf16 v[100:103], v[190:193], v[206:209], v[100:103]
	v_mfma_f32_16x16x32_bf16 v[84:87], v[190:193], v[214:217], v[84:87]
	v_mfma_f32_16x16x32_bf16 v[68:71], v[190:193], v[222:225], v[68:71]
	v_mfma_f32_16x16x32_bf16 v[120:123], v[186:189], v[202:205], v[120:123]
	v_mfma_f32_16x16x32_bf16 v[104:107], v[186:189], v[210:213], v[104:107]
	v_mfma_f32_16x16x32_bf16 v[88:91], v[186:189], v[218:221], v[88:91]
	v_mfma_f32_16x16x32_bf16 v[72:75], v[186:189], v[226:229], v[72:75]
	v_mfma_f32_16x16x32_bf16 v[116:119], v[194:197], v[202:205], v[116:119]
	v_mfma_f32_16x16x32_bf16 v[100:103], v[194:197], v[210:213], v[100:103]
	v_mfma_f32_16x16x32_bf16 v[84:87], v[194:197], v[218:221], v[84:87]
	v_mfma_f32_16x16x32_bf16 v[68:71], v[194:197], v[226:229], v[68:71]
	s_setprio 0
	s_barrier
	s_add_i32 s42, s42, s31
	v_lshl_add_u64 v[178:179], s[26:27], 0, v[2:3]
	s_mov_b32 m0, s42
	ds_read_b128 v[198:201], v165 offset:16384
	ds_read_b128 v[202:205], v165 offset:17408
	ds_read_b128 v[206:209], v165 offset:18432
	ds_read_b128 v[210:213], v165 offset:19456
	ds_read_b128 v[214:217], v165 offset:20480
	ds_read_b128 v[218:221], v165 offset:21504
	ds_read_b128 v[222:225], v165 offset:22528
	ds_read_b128 v[226:229], v165 offset:23552
	global_load_lds_dwordx4 v[178:179], off
	s_add_i32 m0, s42, 0x2000
	s_add_u32 s94, s26, 0x80000
	v_lshl_add_u64 v[180:181], s[26:27], 0, v[0:1]
	s_addc_u32 s95, s27, 0
	s_add_i32 s42, s43, s31
	global_load_lds_dwordx4 v[180:181], off
	v_lshl_add_u64 v[138:139], s[94:95], 0, v[2:3]
	s_mov_b32 m0, s42
	v_lshl_add_u64 v[182:183], s[28:29], 0, v[150:151]
	global_load_lds_dwordx4 v[138:139], off
	v_lshl_add_u64 v[138:139], s[94:95], 0, v[0:1]
	s_add_i32 m0, s42, 0x2000
	v_lshl_add_u64 v[230:231], s[28:29], 0, v[148:149]
	global_load_lds_dwordx4 v[138:139], off
	s_mov_b32 m0, s37
	s_nop 0
	global_load_lds_dwordx4 v[182:183], off
	s_mov_b32 m0, s39
	s_nop 0
	global_load_lds_dwordx4 v[230:231], off
	s_waitcnt vmcnt(8)
	s_waitcnt lgkmcnt(0)
	s_setprio 1
	s_barrier
; #define PG8_STAGE(bufoff, gbase, voff) do { _Pragma("unroll") for (int _i = 0; _i < 2; ++_i) \
;         __builtin_amdgcn_global_load_lds((const unsigned*)((const char*)(gbase) + (voff)[_i]), (PG8_LAS unsigned*)(lds + (bufoff) + ldsw + _i * 8192), 16, 0, 0); } while (0)
; #define PG8_LDA(dst, b, h) do { _Pragma("unroll") for (int m = 0; m < 4; ++m) _Pragma("unroll") for (int k = 0; k < 2; ++k) dst[m][k] = *(const PG8_LAS bf16x8*)(lds + PG8_SA(b, h) + aoff + m * 2048 + k * 1024); } while (0)
; #define PG8_LDB(dst, b, h) do { _Pragma("unroll") for (int n = 0; n < 2; ++n) _Pragma("unroll") for (int k = 0; k < 2; ++k) dst[n][k] = *(const PG8_LAS bf16x8*)(lds + PG8_SB(b, h) + boff + n * 2048 + k * 1024); } while (0)
; #define PG8_MMA(ai, bj, At, Bt) do { __builtin_amdgcn_s_setprio(1); _Pragma("unroll") for (int m = 0; m < 4; ++m) _Pragma("unroll") for (int n = 0; n < 2; ++n) _Pragma("unroll") for (int k = 0; k < 2; ++k) \
;         acc[ai][bj][m][n] = __builtin_amdgcn_mfma_f32_16x16x32_bf16(Bt[n][k], At[m][k], acc[ai][bj][m][n], 0, 0, 0); __builtin_amdgcn_s_setprio(0); } while (0)
; #define PG8_WAIT_V(n) asm volatile("s_waitcnt vmcnt(" #n ")" ::: "memory")
; #define PG8_WAIT_L(n) asm volatile("s_waitcnt lgkmcnt(" #n ")" ::: "memory")
; #define PG8_BAR __builtin_amdgcn_s_barrier()
; #define PG8_SCHED __builtin_amdgcn_sched_barrier(0)
; template <class Epi, class Sched, bool ALIGN_EPI = false, bool SP2 = false>
; __device__ __forceinline__ void gemm_phase(PG8_LAS unsigned char* lds, const Gemm g, const Sched& S, const Epi& E, const int tid) {
;     ...
;             PG8_WAIT_V(8); PG8_WAIT_L(0); PG8_BAR; PG8_MMA(1, 0, At, B0); PG8_MMA(1, 1, At, B1); PG8_BAR; PG8_SCHED;
;             PG8_LDB(B0, 1, 0); PG8_LDB(B1, 1, 1); PG8_SCHED; PG8_LDA(At, 1, 0); PG8_STAGE(PG8_SA(0, 1), a2 + hstep, voffA);
;             PG8_WAIT_V(8); PG8_WAIT_L(0); PG8_BAR; PG8_MMA(0, 0, At, B0); PG8_MMA(0, 1, At, B1); PG8_BAR; PG8_SCHED;
	v_mfma_f32_16x16x32_bf16 v[64:67], v[140:143], v[198:201], v[64:67]
	v_mfma_f32_16x16x32_bf16 v[48:51], v[140:143], v[206:209], v[48:51]
	v_mfma_f32_16x16x32_bf16 v[32:35], v[140:143], v[214:217], v[32:35]
	v_mfma_f32_16x16x32_bf16 v[16:19], v[140:143], v[222:225], v[16:19]
	v_mfma_f32_16x16x32_bf16 v[60:63], v[166:169], v[198:201], v[60:63]
	v_mfma_f32_16x16x32_bf16 v[44:47], v[166:169], v[206:209], v[44:47]
	v_mfma_f32_16x16x32_bf16 v[28:31], v[166:169], v[214:217], v[28:31]
	v_mfma_f32_16x16x32_bf16 v[12:15], v[166:169], v[222:225], v[12:15]
	v_mfma_f32_16x16x32_bf16 v[64:67], v[144:147], v[202:205], v[64:67]
	v_mfma_f32_16x16x32_bf16 v[48:51], v[144:147], v[210:213], v[48:51]
	v_mfma_f32_16x16x32_bf16 v[32:35], v[144:147], v[218:221], v[32:35]
	v_mfma_f32_16x16x32_bf16 v[16:19], v[144:147], v[226:229], v[16:19]
	v_mfma_f32_16x16x32_bf16 v[60:63], v[170:173], v[202:205], v[60:63]
	v_mfma_f32_16x16x32_bf16 v[44:47], v[170:173], v[210:213], v[44:47]
	v_mfma_f32_16x16x32_bf16 v[28:31], v[170:173], v[218:221], v[28:31]
	v_mfma_f32_16x16x32_bf16 v[12:15], v[170:173], v[226:229], v[12:15]
	s_setprio 0
	s_setprio 1
	v_mfma_f32_16x16x32_bf16 v[56:59], v[174:177], v[198:201], v[56:59]
	v_mfma_f32_16x16x32_bf16 v[40:43], v[174:177], v[206:209], v[40:43]
	v_mfma_f32_16x16x32_bf16 v[24:27], v[174:177], v[214:217], v[24:27]
	v_mfma_f32_16x16x32_bf16 v[8:11], v[174:177], v[222:225], v[8:11]
	v_mfma_f32_16x16x32_bf16 v[52:55], v[190:193], v[198:201], v[52:55]
	v_mfma_f32_16x16x32_bf16 v[36:39], v[190:193], v[206:209], v[36:39]
	v_mfma_f32_16x16x32_bf16 v[20:23], v[190:193], v[214:217], v[20:23]
	v_mfma_f32_16x16x32_bf16 v[4:7], v[190:193], v[222:225], v[4:7]
	v_mfma_f32_16x16x32_bf16 v[56:59], v[186:189], v[202:205], v[56:59]
	v_mfma_f32_16x16x32_bf16 v[40:43], v[186:189], v[210:213], v[40:43]
	v_mfma_f32_16x16x32_bf16 v[24:27], v[186:189], v[218:221], v[24:27]
	v_mfma_f32_16x16x32_bf16 v[8:11], v[186:189], v[226:229], v[8:11]
	v_mfma_f32_16x16x32_bf16 v[52:55], v[194:197], v[202:205], v[52:55]
	v_mfma_f32_16x16x32_bf16 v[36:39], v[194:197], v[210:213], v[36:39]
	v_mfma_f32_16x16x32_bf16 v[20:23], v[194:197], v[218:221], v[20:23]
	v_mfma_f32_16x16x32_bf16 v[4:7], v[194:197], v[226:229], v[4:7]
	s_setprio 0
	s_barrier
	s_add_i32 s42, 0, 0x18000
	v_add_u32_e32 v138, s42, v161
	s_add_i32 s43, 0, 0x1c000
	ds_read_b128 v[140:143], v138
	ds_read_b128 v[144:147], v138 offset:1024
	ds_read_b128 v[166:169], v138 offset:2048
	ds_read_b128 v[170:173], v138 offset:3072
	v_add_u32_e32 v138, s43, v161
	ds_read_b128 v[174:177], v138
	ds_read_b128 v[186:189], v138 offset:1024
	ds_read_b128 v[190:193], v138 offset:2048
	ds_read_b128 v[194:197], v138 offset:3072
	s_add_u32 s28, s28, 0x80000
	s_addc_u32 s29, s29, 0
	s_mov_b32 m0, s44
	v_lshl_add_u64 v[138:139], s[28:29], 0, v[150:151]
	ds_read_b128 v[198:201], v165 offset:32768
	ds_read_b128 v[202:205], v165 offset:33792
	ds_read_b128 v[206:209], v165 offset:34816
	ds_read_b128 v[210:213], v165 offset:35840
	ds_read_b128 v[214:217], v165 offset:36864
	ds_read_b128 v[218:221], v165 offset:37888
	ds_read_b128 v[222:225], v165 offset:38912
	ds_read_b128 v[226:229], v165 offset:39936
	global_load_lds_dwordx4 v[138:139], off
	v_lshl_add_u64 v[138:139], s[28:29], 0, v[148:149]
	s_mov_b32 m0, s48
	s_nop 0
	global_load_lds_dwordx4 v[138:139], off
	s_waitcnt vmcnt(8)
	s_waitcnt lgkmcnt(0)
	s_setprio 1
	s_barrier
	v_mfma_f32_16x16x32_bf16 v[134:137], v[140:143], v[198:201], v[134:137]
	v_mfma_f32_16x16x32_bf16 v[112:115], v[140:143], v[206:209], v[112:115]
	v_mfma_f32_16x16x32_bf16 v[96:99], v[140:143], v[214:217], v[96:99]
	v_mfma_f32_16x16x32_bf16 v[80:83], v[140:143], v[222:225], v[80:83]
	v_mfma_f32_16x16x32_bf16 v[124:127], v[166:169], v[198:201], v[124:127]
	v_mfma_f32_16x16x32_bf16 v[108:111], v[166:169], v[206:209], v[108:111]
	v_mfma_f32_16x16x32_bf16 v[92:95], v[166:169], v[214:217], v[92:95]
	v_mfma_f32_16x16x32_bf16 v[76:79], v[166:169], v[222:225], v[76:79]
	v_mfma_f32_16x16x32_bf16 v[136:139], v[144:147], v[202:205], v[134:137]
	v_mfma_f32_16x16x32_bf16 v[112:115], v[144:147], v[210:213], v[112:115]
	v_mfma_f32_16x16x32_bf16 v[96:99], v[144:147], v[218:221], v[96:99]
	v_mfma_f32_16x16x32_bf16 v[80:83], v[144:147], v[226:229], v[80:83]
	v_mfma_f32_16x16x32_bf16 v[124:127], v[170:173], v[202:205], v[124:127]
	v_mfma_f32_16x16x32_bf16 v[108:111], v[170:173], v[210:213], v[108:111]
	v_mfma_f32_16x16x32_bf16 v[92:95], v[170:173], v[218:221], v[92:95]
	v_mfma_f32_16x16x32_bf16 v[76:79], v[170:173], v[226:229], v[76:79]
	s_setprio 0
	s_setprio 1
	v_mfma_f32_16x16x32_bf16 v[120:123], v[174:177], v[198:201], v[120:123]
	v_mfma_f32_16x16x32_bf16 v[104:107], v[174:177], v[206:209], v[104:107]
	v_mfma_f32_16x16x32_bf16 v[88:91], v[174:177], v[214:217], v[88:91]
	v_mfma_f32_16x16x32_bf16 v[72:75], v[174:177], v[222:225], v[72:75]
	v_mfma_f32_16x16x32_bf16 v[116:119], v[190:193], v[198:201], v[116:119]
	v_mfma_f32_16x16x32_bf16 v[100:103], v[190:193], v[206:209], v[100:103]
	v_mfma_f32_16x16x32_bf16 v[84:87], v[190:193], v[214:217], v[84:87]
	v_mfma_f32_16x16x32_bf16 v[68:71], v[190:193], v[222:225], v[68:71]
	v_mfma_f32_16x16x32_bf16 v[120:123], v[186:189], v[202:205], v[120:123]
	v_mfma_f32_16x16x32_bf16 v[104:107], v[186:189], v[210:213], v[104:107]
	v_mfma_f32_16x16x32_bf16 v[88:91], v[186:189], v[218:221], v[88:91]
	v_mfma_f32_16x16x32_bf16 v[72:75], v[186:189], v[226:229], v[72:75]
	v_mfma_f32_16x16x32_bf16 v[116:119], v[194:197], v[202:205], v[116:119]
	v_mfma_f32_16x16x32_bf16 v[100:103], v[194:197], v[210:213], v[100:103]
	v_mfma_f32_16x16x32_bf16 v[84:87], v[194:197], v[218:221], v[84:87]
	v_mfma_f32_16x16x32_bf16 v[68:71], v[194:197], v[226:229], v[68:71]
	s_setprio 0
	s_barrier
; #define PG8_STAGE(bufoff, gbase, voff) do { _Pragma("unroll") for (int _i = 0; _i < 2; ++_i) \
;         __builtin_amdgcn_global_load_lds((const unsigned*)((const char*)(gbase) + (voff)[_i]), (PG8_LAS unsigned*)(lds + (bufoff) + ldsw + _i * 8192), 16, 0, 0); } while (0)
; #define PG8_LDA(dst, b, h) do { _Pragma("unroll") for (int m = 0; m < 4; ++m) _Pragma("unroll") for (int k = 0; k < 2; ++k) dst[m][k] = *(const PG8_LAS bf16x8*)(lds + PG8_SA(b, h) + aoff + m * 2048 + k * 1024); } while (0)
; #define PG8_MMA(ai, bj, At, Bt) do { __builtin_amdgcn_s_setprio(1); _Pragma("unroll") for (int m = 0; m < 4; ++m) _Pragma("unroll") for (int n = 0; n < 2; ++n) _Pragma("unroll") for (int k = 0; k < 2; ++k) \
;         acc[ai][bj][m][n] = __builtin_amdgcn_mfma_f32_16x16x32_bf16(Bt[n][k], At[m][k], acc[ai][bj][m][n], 0, 0, 0); __builtin_amdgcn_s_setprio(0); } while (0)
; #define PG8_WAIT_V(n) asm volatile("s_waitcnt vmcnt(" #n ")" ::: "memory")
; #define PG8_WAIT_L(n) asm volatile("s_waitcnt lgkmcnt(" #n ")" ::: "memory")
; #define PG8_BAR __builtin_amdgcn_s_barrier()
; #define PG8_SCHED __builtin_amdgcn_sched_barrier(0)
; template <class Epi, class Sched, bool ALIGN_EPI = false, bool SP2 = false>
; __device__ __forceinline__ void gemm_phase(PG8_LAS unsigned char* lds, const Gemm g, const Sched& S, const Epi& E, const int tid) {
;     ...
;             PG8_LDA(At, 1, 1); PG8_STAGE(PG8_SB(1, 0), b3, voffB); PG8_STAGE(PG8_SB(1, 1), b3 + hstep, voffB); PG8_STAGE(PG8_SA(1, 0), a3, voffA);
;             PG8_WAIT_V(8); PG8_WAIT_L(0); PG8_BAR; PG8_MMA(1, 0, At, B0); PG8_MMA(1, 1, At, B1); PG8_BAR; PG8_SCHED;
	s_add_i32 s28, s42, s31
	v_lshl_add_u64 v[134:135], v[178:179], 0, s[46:47]
	s_mov_b32 m0, s28
	ds_read_b128 v[198:201], v165 offset:49152
	ds_read_b128 v[202:205], v165 offset:50176
	ds_read_b128 v[206:209], v165 offset:51200
	ds_read_b128 v[210:213], v165 offset:52224
	ds_read_b128 v[214:217], v165 offset:53248
	ds_read_b128 v[218:221], v165 offset:54272
	ds_read_b128 v[222:225], v165 offset:55296
	ds_read_b128 v[226:229], v165 offset:56320
	global_load_lds_dwordx4 v[134:135], off
	s_add_i32 m0, s28, 0x2000
	s_add_u32 s26, s26, 0x80080
	v_lshl_add_u64 v[134:135], v[180:181], 0, s[46:47]
	s_addc_u32 s27, s27, 0
	s_add_i32 s28, s43, s31
	global_load_lds_dwordx4 v[134:135], off
	v_lshl_add_u64 v[134:135], s[26:27], 0, v[2:3]
	s_mov_b32 m0, s28
	s_nop 0
	global_load_lds_dwordx4 v[134:135], off
	v_lshl_add_u64 v[134:135], s[26:27], 0, v[0:1]
	s_add_i32 m0, s28, 0x2000
	s_nop 0
	global_load_lds_dwordx4 v[134:135], off
	v_lshl_add_u64 v[134:135], v[182:183], 0, s[46:47]
	s_mov_b32 m0, s52
	s_nop 0
	global_load_lds_dwordx4 v[134:135], off
	v_lshl_add_u64 v[134:135], v[230:231], 0, s[46:47]
	s_mov_b32 m0, s53
	s_nop 0
	global_load_lds_dwordx4 v[134:135], off
	s_waitcnt vmcnt(8)
	s_waitcnt lgkmcnt(0)
	s_setprio 1
	s_barrier
	v_mfma_f32_16x16x32_bf16 v[64:67], v[140:143], v[198:201], v[64:67]
	v_mfma_f32_16x16x32_bf16 v[48:51], v[140:143], v[206:209], v[48:51]
	v_mfma_f32_16x16x32_bf16 v[32:35], v[140:143], v[214:217], v[32:35]
	v_mfma_f32_16x16x32_bf16 v[16:19], v[140:143], v[222:225], v[16:19]
	v_mfma_f32_16x16x32_bf16 v[60:63], v[166:169], v[198:201], v[60:63]
	v_mfma_f32_16x16x32_bf16 v[44:47], v[166:169], v[206:209], v[44:47]
	v_mfma_f32_16x16x32_bf16 v[28:31], v[166:169], v[214:217], v[28:31]
	v_mfma_f32_16x16x32_bf16 v[12:15], v[166:169], v[222:225], v[12:15]
	v_mfma_f32_16x16x32_bf16 v[64:67], v[144:147], v[202:205], v[64:67]
	v_mfma_f32_16x16x32_bf16 v[48:51], v[144:147], v[210:213], v[48:51]
	v_mfma_f32_16x16x32_bf16 v[32:35], v[144:147], v[218:221], v[32:35]
	v_mfma_f32_16x16x32_bf16 v[16:19], v[144:147], v[226:229], v[16:19]
	v_mfma_f32_16x16x32_bf16 v[60:63], v[170:173], v[202:205], v[60:63]
	v_mfma_f32_16x16x32_bf16 v[44:47], v[170:173], v[210:213], v[44:47]
	v_mfma_f32_16x16x32_bf16 v[28:31], v[170:173], v[218:221], v[28:31]
	v_mfma_f32_16x16x32_bf16 v[12:15], v[170:173], v[226:229], v[12:15]
	s_setprio 0
	s_setprio 1
	v_mfma_f32_16x16x32_bf16 v[56:59], v[174:177], v[198:201], v[56:59]
	v_mfma_f32_16x16x32_bf16 v[40:43], v[174:177], v[206:209], v[40:43]
	v_mfma_f32_16x16x32_bf16 v[24:27], v[174:177], v[214:217], v[24:27]
	v_mfma_f32_16x16x32_bf16 v[8:11], v[174:177], v[222:225], v[8:11]
	v_mfma_f32_16x16x32_bf16 v[52:55], v[190:193], v[198:201], v[52:55]
	v_mfma_f32_16x16x32_bf16 v[36:39], v[190:193], v[206:209], v[36:39]
	v_mfma_f32_16x16x32_bf16 v[20:23], v[190:193], v[214:217], v[20:23]
	v_mfma_f32_16x16x32_bf16 v[4:7], v[190:193], v[222:225], v[4:7]
	v_mfma_f32_16x16x32_bf16 v[56:59], v[186:189], v[202:205], v[56:59]
	v_mfma_f32_16x16x32_bf16 v[40:43], v[186:189], v[210:213], v[40:43]
	v_mfma_f32_16x16x32_bf16 v[24:27], v[186:189], v[218:221], v[24:27]
	v_mfma_f32_16x16x32_bf16 v[8:11], v[186:189], v[226:229], v[8:11]
	v_mfma_f32_16x16x32_bf16 v[52:55], v[194:197], v[202:205], v[52:55]
	v_mfma_f32_16x16x32_bf16 v[36:39], v[194:197], v[210:213], v[36:39]
	v_mfma_f32_16x16x32_bf16 v[20:23], v[194:197], v[218:221], v[20:23]
	v_mfma_f32_16x16x32_bf16 v[4:7], v[194:197], v[226:229], v[4:7]
	s_setprio 0
	s_barrier
	s_add_i32 s51, s51, 2
	s_add_u32 s24, s24, 0x100
	s_addc_u32 s25, s25, 0
	s_add_u32 s23, s23, 0x100
	s_addc_u32 s50, s50, 0
	s_cmp_gt_u32 s51, 29
	s_cbranch_scc1 .LBB0_269
